# NSA importance pass: one barrier + ordered 4-way sum instead of 4 serialized per-head rounds; NSA bias table built at top-k
# speedup vs baseline: 1.0029x; 1.0029x over previous
; #define MFMA32(a, b, c) __builtin_amdgcn_mfma_f32_32x32x16_bf16((a), (b), (c), 0, 0, 0)
; DI float ex2(float x) { return __builtin_amdgcn_exp2f(x); }
; DI float xor32(float v) { return __shfl_xor(v, 32); }
; DI void task_nsa(const P& p, int layer, int task, bf16_t* sm, int dm) {
;     ...
;     for (int ct = 0; ct < nct; ++ct, ++itc) {
;       bf16_t* Kl = sm + (itc & 1) * 9216; bf16_t* Vl = Kl + 4608;
;       kv_lstore(R, Kl, Vl);
;       if (ct + 1 < nct) kv_gload(R, kg, 64, vg, 256, (ct + 1) * 64);
;       __syncthreads();
;       float val[2][4];
; #pragma unroll
;       for (int st = 0; st < 2; ++st) {
;         f32x16 s;
; #pragma unroll
;         for (int i = 0; i < 16; ++i) s[i] = 0.f;
; #pragma unroll
;         for (int ks = 0; ks < 4; ++ks) {
;           bf16x8 kf = *(const bf16x8*)(Kl + (st * 32 + lr) * 72 + ks * 16 + lh * 8);
;           s = MFMA32(kf, q[ks], s);
;         }
;         float pq[4], pl[4], other[4];
; #pragma unroll
;         for (int g4 = 0; g4 < 4; ++g4) {
;           float sum = 0.f, last = 0.f;
; #pragma unroll
;           for (int e = 0; e < 4; ++e) {
;             const int cc = ct * 64 + st * 32 + 8 * g4 + 4 * lh + e;
;             const float pe = (16 * cc + 31 <= qp) ? ex2(s[4 * g4 + e] - m) * inv : 0.f;
;             sum += pe; last = pe;
;           }
;           pq[g4] = sum; pl[g4] = last;
;         }
; #pragma unroll
;         for (int g4 = 0; g4 < 4; ++g4) other[g4] = xor32(pl[g4]);
;         val[st][0] = pq[0] + (lh ? other[0] : carry);
;         val[st][1] = pq[1] + (lh ? other[1] : other[0]);
;         val[st][2] = pq[2] + (lh ? other[2] : other[1]);
;         val[st][3] = pq[3] + (lh ? other[3] : other[2]);
;         carry = other[3];
.LBB0_676:
	v_add3_u32 v35, s0, v27, v24
	s_waitcnt lgkmcnt(0)
	s_barrier
	ds_read_b128 v[0:3], v35
	ds_read_b128 v[36:39], v35 offset:32
	s_waitcnt lgkmcnt(1)
	v_mfma_f32_32x32x16_bf16 v[0:15], v[0:3], v[64:67], 0
	v_add_u32_e32 v29, 0xfffffc50, v26
	v_cmp_le_i32_e64 s[0:1], v29, v135
	v_add_u32_e32 v29, 0xfffffc60, v26
	s_waitcnt lgkmcnt(0)
	v_mfma_f32_32x32x16_bf16 v[0:15], v[36:39], v[68:71], v[0:15]
	ds_read_b128 v[36:39], v35 offset:64
	s_waitcnt lgkmcnt(0)
	v_mfma_f32_32x32x16_bf16 v[0:15], v[36:39], v[72:75], v[0:15]
	ds_read_b128 v[36:39], v35 offset:96
	s_waitcnt lgkmcnt(0)
	v_mfma_f32_32x32x16_bf16 v[0:15], v[36:39], v[76:79], v[0:15]
	ds_read_b128 v[38:41], v35 offset:4640
	s_nop 10
	v_sub_f32_e32 v0, v0, v33
	v_exp_f32_e32 v0, v0
	v_sub_f32_e32 v1, v1, v33
	v_exp_f32_e32 v1, v1
	v_sub_f32_e32 v2, v2, v33
	v_fma_f32 v0, v32, v0, 0
	v_exp_f32_e32 v2, v2
	v_cndmask_b32_e64 v0, 0, v0, s[0:1]
	v_mul_f32_e32 v1, v32, v1
	v_cmp_le_i32_e64 s[0:1], v29, v135
	v_mul_f32_e32 v2, v32, v2
	s_nop 0
	v_cndmask_b32_e64 v1, 0, v1, s[0:1]
	v_add_f32_e32 v0, v1, v0
	v_add_u32_e32 v1, 0xfffffc70, v26
	v_cmp_le_i32_e64 s[0:1], v1, v135
	s_nop 1
	v_cndmask_b32_e64 v1, 0, v2, s[0:1]
	v_sub_f32_e32 v2, v3, v33
	v_exp_f32_e32 v2, v2
	v_sub_f32_e32 v3, v4, v33
	v_exp_f32_e32 v3, v3
	v_add_f32_e32 v0, v1, v0
	v_add_u32_e32 v1, 0xfffffc80, v26
	v_sub_f32_e32 v4, v5, v33
	v_mul_f32_e32 v2, v32, v2
	v_cmp_le_i32_e64 s[0:1], v1, v135
	v_exp_f32_e32 v4, v4
	v_fma_f32 v3, v32, v3, 0
	v_cndmask_b32_e64 v1, 0, v2, s[0:1]
	v_add_u32_e32 v2, 0xfffffcd0, v26
	v_cmp_le_i32_e64 s[0:1], v2, v135
	v_mul_f32_e32 v4, v32, v4
	v_sub_f32_e32 v5, v8, v33
	v_cndmask_b32_e64 v2, 0, v3, s[0:1]
	v_add_u32_e32 v3, 0xfffffce0, v26
	v_cmp_le_i32_e64 s[0:1], v3, v135
	v_exp_f32_e32 v5, v5
	v_sub_f32_e32 v8, v13, v33
	v_cndmask_b32_e64 v3, 0, v4, s[0:1]
	v_sub_f32_e32 v4, v6, v33
	v_exp_f32_e32 v4, v4
	v_add_f32_e32 v2, v3, v2
	v_add_u32_e32 v3, 0xfffffcf0, v26
	v_cmp_le_i32_e64 s[0:1], v3, v135
	v_mul_f32_e32 v4, v32, v4
	v_sub_f32_e32 v6, v9, v33
	v_cndmask_b32_e64 v3, 0, v4, s[0:1]
	v_sub_f32_e32 v4, v7, v33
	v_exp_f32_e32 v4, v4
	v_add_f32_e32 v2, v3, v2
	v_add_u32_e32 v3, 0xfffffd00, v26
	v_cmp_le_i32_e64 s[0:1], v3, v135
	v_mul_f32_e32 v4, v32, v4
	v_exp_f32_e32 v6, v6
	v_cndmask_b32_e64 v3, 0, v4, s[0:1]
	v_add_u32_e32 v4, 0xfffffd50, v26
	v_fma_f32 v5, v32, v5, 0
	v_cmp_le_i32_e64 s[0:1], v4, v135
	v_mul_f32_e32 v6, v32, v6
	v_sub_f32_e32 v7, v12, v33
	v_cndmask_b32_e64 v4, 0, v5, s[0:1]
	v_add_u32_e32 v5, 0xfffffd60, v26
	v_cmp_le_i32_e64 s[0:1], v5, v135
	v_exp_f32_e32 v7, v7
	v_exp_f32_e32 v8, v8
	v_cndmask_b32_e64 v5, 0, v6, s[0:1]
	v_sub_f32_e32 v6, v10, v33
	v_exp_f32_e32 v6, v6
	v_add_f32_e32 v4, v5, v4
	v_add_u32_e32 v5, 0xfffffd70, v26
	v_cmp_le_i32_e64 s[0:1], v5, v135
	v_mul_f32_e32 v6, v32, v6
	v_fma_f32 v7, v32, v7, 0
	v_cndmask_b32_e64 v5, 0, v6, s[0:1]
	v_sub_f32_e32 v6, v11, v33
	v_exp_f32_e32 v6, v6
	v_add_f32_e32 v4, v5, v4
	v_add_u32_e32 v5, 0xfffffd80, v26
	v_cmp_le_i32_e64 s[0:1], v5, v135
	v_mul_f32_e32 v6, v32, v6
	v_mul_f32_e32 v8, v32, v8
	v_cndmask_b32_e64 v5, 0, v6, s[0:1]
	v_add_u32_e32 v6, 0xfffffdd0, v26
	v_cmp_le_i32_e64 s[0:1], v6, v135
	v_add_f32_e32 v0, v1, v0
	ds_bpermute_b32 v1, v91, v1
	v_cndmask_b32_e64 v6, 0, v7, s[0:1]
	v_add_u32_e32 v7, 0xfffffde0, v26
	v_cmp_le_i32_e64 s[0:1], v7, v135
	v_add_f32_e32 v2, v3, v2
	ds_bpermute_b32 v3, v91, v3
	v_cndmask_b32_e64 v7, 0, v8, s[0:1]
	v_sub_f32_e32 v8, v14, v33
	v_exp_f32_e32 v8, v8
	v_add_f32_e32 v6, v7, v6
	v_add_u32_e32 v7, 0xfffffdf0, v26
	v_cmp_le_i32_e64 s[0:1], v7, v135
	v_mul_f32_e32 v8, v32, v8
	v_add_f32_e32 v4, v5, v4
	v_cndmask_b32_e64 v7, 0, v8, s[0:1]
	v_sub_f32_e32 v8, v15, v33
	v_exp_f32_e32 v8, v8
	v_add_f32_e32 v6, v7, v6
	v_add_u32_e32 v7, 0xfffffe00, v26
	v_cmp_le_i32_e64 s[0:1], v7, v135
	v_mul_f32_e32 v8, v32, v8
	ds_bpermute_b32 v5, v91, v5
	v_cndmask_b32_e64 v7, 0, v8, s[0:1]
	ds_bpermute_b32 v36, v91, v7
	v_add_f32_e32 v6, v7, v6
	s_waitcnt lgkmcnt(3)
	v_cndmask_b32_e32 v7, v1, v28, vcc
	v_add_f32_e32 v31, v7, v0
	s_waitcnt lgkmcnt(2)
	v_cndmask_b32_e32 v0, v3, v1, vcc
	v_add_f32_e32 v34, v0, v2
	s_waitcnt lgkmcnt(1)
	v_cndmask_b32_e32 v0, v5, v3, vcc
	v_add_f32_e32 v29, v0, v4
	s_waitcnt lgkmcnt(0)
	v_cndmask_b32_e32 v0, v36, v5, vcc
	v_add_f32_e32 v30, v0, v6
	ds_read_b128 v[0:3], v35 offset:4608
	s_waitcnt lgkmcnt(0)
	v_mfma_f32_32x32x16_bf16 v[0:15], v[0:3], v[64:67], 0
	v_add_u32_e32 v28, 0xfffffe50, v26
	v_cmp_le_i32_e64 s[0:1], v28, v135
	v_add_u32_e32 v28, 0xfffffe60, v26
	v_mfma_f32_32x32x16_bf16 v[0:15], v[38:41], v[68:71], v[0:15]
	ds_read_b128 v[38:41], v35 offset:4672
	s_waitcnt lgkmcnt(0)
	v_mfma_f32_32x32x16_bf16 v[0:15], v[38:41], v[72:75], v[0:15]
	ds_read_b128 v[38:41], v35 offset:4704
	s_waitcnt lgkmcnt(0)
; DI void task_nsa(const P& p, int layer, int task, bf16_t* sm, int dm) {
;     ...
;       for (int w = 0; w < 4; ++w) {
;         if (hr == w) {
; #pragma unroll
;           for (int st = 0; st < 2; ++st)
; #pragma unroll
;             for (int g4 = 0; g4 < 4; ++g4) cbuf[(ct * 16 + st * 8 + 2 * g4 + lh) * 65 + ql] += val[st][g4];
;         }
;         __syncthreads();
;       }
	v_mfma_f32_32x32x16_bf16 v[0:15], v[38:41], v[76:79], v[0:15]
	s_nop 11
	v_sub_f32_e32 v0, v0, v33
	v_exp_f32_e32 v0, v0
	v_sub_f32_e32 v1, v1, v33
	v_exp_f32_e32 v1, v1
	v_sub_f32_e32 v2, v2, v33
	v_fma_f32 v0, v32, v0, 0
	v_exp_f32_e32 v2, v2
	v_cndmask_b32_e64 v0, 0, v0, s[0:1]
	v_mul_f32_e32 v1, v32, v1
	v_cmp_le_i32_e64 s[0:1], v28, v135
	v_mul_f32_e32 v2, v32, v2
	s_nop 0
	v_cndmask_b32_e64 v1, 0, v1, s[0:1]
	v_add_f32_e32 v0, v1, v0
	v_add_u32_e32 v1, 0xfffffe70, v26
	v_cmp_le_i32_e64 s[0:1], v1, v135
	s_nop 1
	v_cndmask_b32_e64 v1, 0, v2, s[0:1]
	v_sub_f32_e32 v2, v3, v33
	v_exp_f32_e32 v2, v2
	v_sub_f32_e32 v3, v4, v33
	v_exp_f32_e32 v3, v3
	v_add_f32_e32 v0, v1, v0
	v_add_u32_e32 v1, 0xfffffe80, v26
	v_sub_f32_e32 v4, v5, v33
	v_mul_f32_e32 v2, v32, v2
	v_cmp_le_i32_e64 s[0:1], v1, v135
	v_exp_f32_e32 v4, v4
	v_fma_f32 v3, v32, v3, 0
	v_cndmask_b32_e64 v1, 0, v2, s[0:1]
	v_add_u32_e32 v2, 0xfffffed0, v26
	v_cmp_le_i32_e64 s[0:1], v2, v135
	v_mul_f32_e32 v4, v32, v4
	v_sub_f32_e32 v5, v8, v33
	v_cndmask_b32_e64 v2, 0, v3, s[0:1]
	v_add_u32_e32 v3, 0xfffffee0, v26
	v_cmp_le_i32_e64 s[0:1], v3, v135
	v_exp_f32_e32 v5, v5
	v_sub_f32_e32 v8, v13, v33
	v_cndmask_b32_e64 v3, 0, v4, s[0:1]
	v_sub_f32_e32 v4, v6, v33
	v_exp_f32_e32 v4, v4
	v_add_f32_e32 v2, v3, v2
	v_add_u32_e32 v3, 0xfffffef0, v26
	v_cmp_le_i32_e64 s[0:1], v3, v135
	v_mul_f32_e32 v4, v32, v4
	v_sub_f32_e32 v6, v9, v33
	v_cndmask_b32_e64 v3, 0, v4, s[0:1]
	v_sub_f32_e32 v4, v7, v33
	v_exp_f32_e32 v4, v4
	v_add_f32_e32 v2, v3, v2
	v_add_u32_e32 v3, 0xffffff00, v26
	v_cmp_le_i32_e64 s[0:1], v3, v135
	v_mul_f32_e32 v4, v32, v4
	v_exp_f32_e32 v6, v6
	v_cndmask_b32_e64 v3, 0, v4, s[0:1]
	v_add_u32_e32 v4, 0xffffff50, v26
	v_fma_f32 v5, v32, v5, 0
	v_cmp_le_i32_e64 s[0:1], v4, v135
	v_mul_f32_e32 v6, v32, v6
	v_sub_f32_e32 v7, v12, v33
	v_cndmask_b32_e64 v4, 0, v5, s[0:1]
	v_add_u32_e32 v5, 0xffffff60, v26
	v_cmp_le_i32_e64 s[0:1], v5, v135
	v_exp_f32_e32 v7, v7
	v_exp_f32_e32 v8, v8
	v_cndmask_b32_e64 v5, 0, v6, s[0:1]
	v_sub_f32_e32 v6, v10, v33
	v_exp_f32_e32 v6, v6
	v_add_f32_e32 v4, v5, v4
	v_add_u32_e32 v5, 0xffffff70, v26
	v_cmp_le_i32_e64 s[0:1], v5, v135
	v_mul_f32_e32 v6, v32, v6
	v_fma_f32 v7, v32, v7, 0
	v_cndmask_b32_e64 v5, 0, v6, s[0:1]
	v_sub_f32_e32 v6, v11, v33
	v_exp_f32_e32 v6, v6
	v_add_f32_e32 v4, v5, v4
	v_add_u32_e32 v5, 0xffffff80, v26
	v_cmp_le_i32_e64 s[0:1], v5, v135
	v_mul_f32_e32 v6, v32, v6
	v_mul_f32_e32 v8, v32, v8
	v_cndmask_b32_e64 v5, 0, v6, s[0:1]
	v_add_f32_e32 v6, v5, v4
	v_subrev_u32_e32 v4, 48, v26
	v_cmp_le_i32_e64 s[0:1], v4, v135
	v_add_f32_e32 v0, v1, v0
	ds_bpermute_b32 v1, v91, v1
	v_cndmask_b32_e64 v4, 0, v7, s[0:1]
	v_subrev_u32_e32 v7, 32, v26
	v_cmp_le_i32_e64 s[0:1], v7, v135
	ds_bpermute_b32 v9, v91, v3
	ds_bpermute_b32 v5, v91, v5
	v_cndmask_b32_e64 v7, 0, v8, s[0:1]
	v_sub_f32_e32 v8, v14, v33
	v_exp_f32_e32 v8, v8
	v_add_f32_e32 v4, v7, v4
	v_add_u32_e32 v7, -16, v26
	v_cmp_le_i32_e64 s[0:1], v7, v135
	v_mul_f32_e32 v8, v32, v8
	v_add_f32_e32 v2, v3, v2
	v_cndmask_b32_e64 v7, 0, v8, s[0:1]
	v_add_f32_e32 v4, v7, v4
	v_sub_f32_e32 v7, v15, v33
	v_exp_f32_e32 v7, v7
	v_cmp_le_i32_e64 s[0:1], v26, v135
	s_waitcnt lgkmcnt(2)
	v_cndmask_b32_e32 v3, v1, v36, vcc
	v_add_f32_e32 v3, v3, v0
	v_mul_f32_e32 v7, v32, v7
	v_cndmask_b32_e64 v7, 0, v7, s[0:1]
	ds_bpermute_b32 v28, v91, v7
	s_waitcnt lgkmcnt(2)
	v_cndmask_b32_e32 v0, v9, v1, vcc
	v_add_f32_e32 v8, v7, v4
	v_add_f32_e32 v4, v0, v2
	s_waitcnt lgkmcnt(1)
	v_cndmask_b32_e32 v0, v5, v9, vcc
	s_waitcnt lgkmcnt(0)
	v_cndmask_b32_e32 v1, v28, v5, vcc
	v_add_f32_e32 v0, v0, v6
	v_add_f32_e32 v1, v1, v8
	v_add_u32_e32 v6, 0x400, v25
	v_add_u32_e32 v5, 0x800, v25
	v_add_u32_e32 v2, 0xc00, v25
	v_readfirstlane_b32 s36, v131
	v_readfirstlane_b32 s37, v130
	s_nop 3
	s_lshr_b32 s38, s37, 2
	s_cmp_eq_u32 s36, 0
	s_cbranch_scc0 .Lcb_scratch
	ds_write2_b32 v25, v31, v34 offset1:130
	ds_write2_b32 v6, v29, v30 offset0:4 offset1:134
	ds_write2_b32 v5, v3, v4 offset0:8 offset1:138
	ds_write2_b32 v2, v0, v1 offset0:12 offset1:142
	s_branch .Lcb_join
.Lcb_scratch:
	s_sub_u32 s42, s36, 1
	s_lshl_b32 s42, s42, 12
	s_lshl_b32 s43, s38, 11
	s_add_u32 s42, s42, s43
	s_add_u32 s42, s42, 0x1e000
	v_lshl_add_u32 v140, v129, 2, s42
	ds_write2st64_b32 v140, v31, v34 offset0:0 offset1:1
	ds_write2st64_b32 v140, v29, v30 offset0:2 offset1:3
	ds_write2st64_b32 v140, v3, v4 offset0:4 offset1:5
	ds_write2st64_b32 v140, v0, v1 offset0:6 offset1:7
.Lcb_join:
	s_waitcnt lgkmcnt(0)
	s_barrier
	s_mul_i32 s42, s36, 0x410
	v_add_u32_e32 v141, s42, v25
	s_lshl_b32 s43, s38, 11
	s_lshl_b32 s42, s36, 9
	s_add_u32 s42, s42, s43
	s_add_u32 s42, s42, 0x1e000
	v_lshl_add_u32 v140, v129, 2, s42
	ds_read2_b32 v[142:143], v141 offset1:130
	ds_read2st64_b32 v[144:145], v140 offset1:1
	ds_read2st64_b32 v[146:147], v140 offset0:16 offset1:17
	ds_read2st64_b32 v[148:149], v140 offset0:32 offset1:33
	s_waitcnt lgkmcnt(2)
	v_add_f32_e32 v142, v142, v144
	v_add_f32_e32 v143, v143, v145
	s_waitcnt lgkmcnt(1)
	v_add_f32_e32 v142, v142, v146
	v_add_f32_e32 v143, v143, v147
	s_waitcnt lgkmcnt(0)
	v_add_f32_e32 v142, v142, v148
	v_add_f32_e32 v143, v143, v149
	ds_write2_b32 v141, v142, v143 offset1:130
	s_branch .LBB0_673
; DI void task_nsa(const P& p, int layer, int task, bf16_t* sm, int dm) {
;     ...
;   for (int i = tid; i < 4 * 129; i += NTHR) {
;     const int r = i / 129, d = i % 129;
;     tabs[r * 132 + d] = ((const float*)(p.ws + O_TABS))[(12 + g * 4 + r) * 132 + d];
;   }
;     ...
;   for (int qi = 0; qi < 8; ++qi) {
;     const int qq = wv * 8 + qi, qpos = q0 + qq, j = lane, cur = qpos >> 6;
;     const float imp = cbuf[j * 65 + qq];
;     const bool valid = j <= cur;
;     const bool forced = (j == 0) || (j == cur) || (j == cur - 1);
;     const float score = valid ? imp + (forced ? 1e4f : 0.f) : -1e30f;
.LBB0_684:
	v_mul_u32_u24_e32 v0, 0x210, v131
	v_readfirstlane_b32 s28, v130
	s_lshr_b32 s9, s25, 6
	v_lshlrev_b32_e32 v171, 2, v129
	s_mul_i32 s30, s28, 0x820
	v_add_u32_e32 v172, s30, v171
	v_lshl_add_u32 v165, v129, 3, s28
	s_waitcnt lgkmcnt(0)
	s_barrier
	v_mov_b32_e32 v246, 0xf149f2ca
	v_lshlrev_b32_e32 v244, 2, v195
	v_add_u32_e32 v244, 0x1e000, v244
	s_waitcnt vmcnt(0)
	v_cmp_gt_u32_e64 s[98:99], s101, v247
	s_nop 1
	v_cndmask_b32_e64 v196, v246, v196, s[98:99]
	v_cndmask_b32_e64 v198, v246, v198, s[98:99]
	v_cndmask_b32_e64 v200, v246, v200, s[98:99]
	v_cndmask_b32_e64 v202, v246, v202, s[98:99]
	v_cmp_gt_u32_e64 s[98:99], s101, v248
	s_nop 1
	v_cndmask_b32_e64 v197, v246, v197, s[98:99]
	v_cndmask_b32_e64 v199, v246, v199, s[98:99]
	v_cndmask_b32_e64 v201, v246, v201, s[98:99]
	v_cndmask_b32_e64 v203, v246, v203, s[98:99]
	ds_write_b32 v244, v196
	ds_write_b32 v244, v197 offset:2048
	ds_write_b32 v244, v198 offset:4096
	ds_write_b32 v244, v199 offset:6144
	ds_write_b32 v244, v200 offset:8192
	ds_write_b32 v244, v201 offset:10240
	ds_write_b32 v244, v202 offset:12288
	ds_write_b32 v244, v203 offset:14336
	ds_read_b32 v116, v172 offset:39168
	ds_read_b32 v117, v172 offset:39428
	ds_read_b32 v118, v172 offset:39688
	ds_read_b32 v119, v172 offset:39948
	ds_read_b32 v120, v172 offset:40208
	ds_read_b32 v121, v172 offset:40468
	ds_read_b32 v122, v172 offset:40728
	ds_read_b32 v123, v172 offset:40988
	s_lshl_b32 s31, s28, 3
	s_sub_i32 s32, s9, s31
	s_cmp_lt_u32 s32, 2
	s_cselect_b32 s36, 0x461c4000, 0
	s_cmp_eq_u32 s31, 0
	s_cselect_b32 s36, 0x461c4000, s36
	s_cmp_ge_i32 s32, 0
	s_cselect_b64 s[48:49], -1, 0
	s_waitcnt lgkmcnt(7)
	v_add_f32_e32 v116, s36, v116
	v_cndmask_b32_e64 v116, v232, v116, s[48:49]
	ds_write_b32 v172, v116 offset:39168
	s_lshl_b32 s31, s28, 3
	s_add_u32 s31, s31, 1
	s_sub_i32 s32, s9, s31
	s_cmp_lt_u32 s32, 2
	s_cselect_b32 s36, 0x461c4000, 0
	s_cmp_eq_u32 s31, 0
	s_cselect_b32 s36, 0x461c4000, s36
	s_cmp_ge_i32 s32, 0
	s_cselect_b64 s[48:49], -1, 0
	s_waitcnt lgkmcnt(7)
	v_add_f32_e32 v117, s36, v117
	v_cndmask_b32_e64 v117, v232, v117, s[48:49]
	ds_write_b32 v172, v117 offset:39428
	s_lshl_b32 s31, s28, 3
	s_add_u32 s31, s31, 2
	s_sub_i32 s32, s9, s31
	s_cmp_lt_u32 s32, 2
	s_cselect_b32 s36, 0x461c4000, 0
	s_cmp_eq_u32 s31, 0
	s_cselect_b32 s36, 0x461c4000, s36
	s_cmp_ge_i32 s32, 0
	s_cselect_b64 s[48:49], -1, 0
	s_waitcnt lgkmcnt(7)
	v_add_f32_e32 v118, s36, v118
	v_cndmask_b32_e64 v118, v232, v118, s[48:49]
	ds_write_b32 v172, v118 offset:39688
	s_lshl_b32 s31, s28, 3
	s_add_u32 s31, s31, 3
	s_sub_i32 s32, s9, s31
	s_cmp_lt_u32 s32, 2
	s_cselect_b32 s36, 0x461c4000, 0
	s_cmp_eq_u32 s31, 0
	s_cselect_b32 s36, 0x461c4000, s36
	s_cmp_ge_i32 s32, 0
	s_cselect_b64 s[48:49], -1, 0
	s_waitcnt lgkmcnt(7)
	v_add_f32_e32 v119, s36, v119
	v_cndmask_b32_e64 v119, v232, v119, s[48:49]
	ds_write_b32 v172, v119 offset:39948
	s_lshl_b32 s31, s28, 3
	s_add_u32 s31, s31, 4
	s_sub_i32 s32, s9, s31
	s_cmp_lt_u32 s32, 2
	s_cselect_b32 s36, 0x461c4000, 0
	s_cmp_eq_u32 s31, 0
	s_cselect_b32 s36, 0x461c4000, s36
	s_cmp_ge_i32 s32, 0
	s_cselect_b64 s[48:49], -1, 0
	s_waitcnt lgkmcnt(7)
	v_add_f32_e32 v120, s36, v120
	v_cndmask_b32_e64 v120, v232, v120, s[48:49]
	ds_write_b32 v172, v120 offset:40208
	s_lshl_b32 s31, s28, 3
	s_add_u32 s31, s31, 5
	s_sub_i32 s32, s9, s31
	s_cmp_lt_u32 s32, 2
	s_cselect_b32 s36, 0x461c4000, 0
	s_cmp_eq_u32 s31, 0
	s_cselect_b32 s36, 0x461c4000, s36
	s_cmp_ge_i32 s32, 0
	s_cselect_b64 s[48:49], -1, 0
	s_waitcnt lgkmcnt(7)
	v_add_f32_e32 v121, s36, v121
	v_cndmask_b32_e64 v121, v232, v121, s[48:49]
	ds_write_b32 v172, v121 offset:40468
	s_lshl_b32 s31, s28, 3
	s_add_u32 s31, s31, 6
	s_sub_i32 s32, s9, s31
	s_cmp_lt_u32 s32, 2
	s_cselect_b32 s36, 0x461c4000, 0
	s_cmp_eq_u32 s31, 0
	s_cselect_b32 s36, 0x461c4000, s36
	s_cmp_ge_i32 s32, 0
	s_cselect_b64 s[48:49], -1, 0
	s_waitcnt lgkmcnt(7)
	v_add_f32_e32 v122, s36, v122
	v_cndmask_b32_e64 v122, v232, v122, s[48:49]
	ds_write_b32 v172, v122 offset:40728
	s_lshl_b32 s31, s28, 3
	s_add_u32 s31, s31, 7
	s_sub_i32 s32, s9, s31
	s_cmp_lt_u32 s32, 2
	s_cselect_b32 s36, 0x461c4000, 0
	s_cmp_eq_u32 s31, 0
	s_cselect_b32 s36, 0x461c4000, s36
	s_cmp_ge_i32 s32, 0
	s_cselect_b64 s[48:49], -1, 0
	s_waitcnt lgkmcnt(7)
	v_add_f32_e32 v123, s36, v123
	v_cndmask_b32_e64 v123, v232, v123, s[48:49]
	ds_write_b32 v172, v123 offset:40988
	s_waitcnt lgkmcnt(0)
	s_barrier
; DI void task_nsa(const P& p, int layer, int task, bf16_t* sm, int dm) {
;     ...
;     const float imp = cbuf[j * 65 + qq];
;     const bool valid = j <= cur;
;     const bool forced = (j == 0) || (j == cur) || (j == cur - 1);
;     const float score = valid ? imp + (forced ? 1e4f : 0.f) : -1e30f;
;     int rank = 0;
; #pragma unroll 4
;     for (int jp = 0; jp < 64; ++jp) {
;       const float sj = __int_as_float(__builtin_amdgcn_readlane(__float_as_int(score), jp));
;       rank += ((sj > score) || (sj == score && jp < j)) ? 1 : 0;
;     }
;     const unsigned long long mk = __ballot(rank < 16);
	ds_read_b32 v16, v171 offset:39168
	ds_read_b32 v17, v171 offset:39428
	ds_read_b32 v18, v171 offset:39688
	ds_read_b32 v19, v171 offset:39948
	ds_read_b32 v20, v171 offset:40208
	ds_read_b32 v21, v171 offset:40468
	ds_read_b32 v22, v171 offset:40728
	ds_read_b32 v23, v171 offset:40988
	v_mov_b32_e32 v156, 0
	v_mov_b32_e32 v157, 0
	v_mov_b32_e32 v158, 0
	v_mov_b32_e32 v159, 0
	v_mov_b32_e32 v160, 0
	v_mov_b32_e32 v161, 0
	v_mov_b32_e32 v162, 0
	v_mov_b32_e32 v163, 0
	ds_read_b32 v24, v171 offset:41248
	ds_read_b32 v25, v171 offset:41508
	ds_read_b32 v26, v171 offset:41768
	ds_read_b32 v27, v171 offset:42028
	ds_read_b32 v28, v171 offset:42288
	ds_read_b32 v29, v171 offset:42548
	ds_read_b32 v30, v171 offset:42808
	ds_read_b32 v31, v171 offset:43068
	s_cmp_lt_u32 0, s28
	s_cselect_b32 s31, 1, 0
	s_cmp_le_u32 0, s28
	s_cselect_b32 s32, 1, 0
	v_subrev_u32_e32 v140, s31, v116
	v_subrev_u32_e32 v141, s31, v117
	v_subrev_u32_e32 v142, s31, v118
	v_subrev_u32_e32 v143, s31, v119
	v_subrev_u32_e32 v144, s31, v120
	v_subrev_u32_e32 v145, s31, v121
	v_subrev_u32_e32 v146, s31, v122
	v_subrev_u32_e32 v147, s31, v123
	v_subrev_u32_e32 v148, s32, v116
	v_subrev_u32_e32 v149, s32, v117
	v_subrev_u32_e32 v150, s32, v118
	v_subrev_u32_e32 v151, s32, v119
	v_subrev_u32_e32 v152, s32, v120
	v_subrev_u32_e32 v153, s32, v121
	v_subrev_u32_e32 v154, s32, v122
	v_subrev_u32_e32 v155, s32, v123
	s_waitcnt lgkmcnt(8)
	v_cmp_gt_i32_e64 s[72:73], v16, v140
	v_cmp_gt_i32_e64 s[74:75], v16, v149
	v_cmp_gt_i32_e64 s[76:77], v16, v150
	v_addc_co_u32_e64 v156, s[42:43], 0, v156, s[72:73]
	v_cmp_gt_i32_e64 s[50:51], v16, v151
	v_addc_co_u32_e64 v157, s[42:43], 0, v157, s[74:75]
	v_cmp_gt_i32_e64 s[72:73], v16, v152
	v_addc_co_u32_e64 v158, s[42:43], 0, v158, s[76:77]
	v_cmp_gt_i32_e64 s[74:75], v16, v153
	v_addc_co_u32_e64 v159, s[42:43], 0, v159, s[50:51]
	v_cmp_gt_i32_e64 s[76:77], v16, v154
	v_addc_co_u32_e64 v160, s[42:43], 0, v160, s[72:73]
	v_cmp_gt_i32_e64 s[50:51], v16, v155
	v_addc_co_u32_e64 v161, s[42:43], 0, v161, s[74:75]
	v_cmp_gt_i32_e64 s[72:73], v17, v140
	v_addc_co_u32_e64 v162, s[42:43], 0, v162, s[76:77]
	v_cmp_gt_i32_e64 s[74:75], v17, v141
	v_addc_co_u32_e64 v163, s[42:43], 0, v163, s[50:51]
	v_cmp_gt_i32_e64 s[76:77], v17, v150
	v_addc_co_u32_e64 v156, s[42:43], 0, v156, s[72:73]
	v_cmp_gt_i32_e64 s[50:51], v17, v151
	v_addc_co_u32_e64 v157, s[42:43], 0, v157, s[74:75]
	v_cmp_gt_i32_e64 s[72:73], v17, v152
	v_addc_co_u32_e64 v158, s[42:43], 0, v158, s[76:77]
	v_cmp_gt_i32_e64 s[74:75], v17, v153
	v_addc_co_u32_e64 v159, s[42:43], 0, v159, s[50:51]
	v_cmp_gt_i32_e64 s[76:77], v17, v154
	v_addc_co_u32_e64 v160, s[42:43], 0, v160, s[72:73]
	v_cmp_gt_i32_e64 s[50:51], v17, v155
	v_addc_co_u32_e64 v161, s[42:43], 0, v161, s[74:75]
	v_cmp_gt_i32_e64 s[72:73], v18, v140
	v_addc_co_u32_e64 v162, s[42:43], 0, v162, s[76:77]
	v_cmp_gt_i32_e64 s[74:75], v18, v141
	v_addc_co_u32_e64 v163, s[42:43], 0, v163, s[50:51]
	v_cmp_gt_i32_e64 s[76:77], v18, v142
	v_addc_co_u32_e64 v156, s[42:43], 0, v156, s[72:73]
	v_cmp_gt_i32_e64 s[50:51], v18, v151
	v_addc_co_u32_e64 v157, s[42:43], 0, v157, s[74:75]
	v_cmp_gt_i32_e64 s[72:73], v18, v152
	v_addc_co_u32_e64 v158, s[42:43], 0, v158, s[76:77]
	v_cmp_gt_i32_e64 s[74:75], v18, v153
	v_addc_co_u32_e64 v159, s[42:43], 0, v159, s[50:51]
	v_cmp_gt_i32_e64 s[76:77], v18, v154
	v_addc_co_u32_e64 v160, s[42:43], 0, v160, s[72:73]
	v_cmp_gt_i32_e64 s[50:51], v18, v155
	v_addc_co_u32_e64 v161, s[42:43], 0, v161, s[74:75]
	v_cmp_gt_i32_e64 s[72:73], v19, v140
	v_addc_co_u32_e64 v162, s[42:43], 0, v162, s[76:77]
	v_cmp_gt_i32_e64 s[74:75], v19, v141
	v_addc_co_u32_e64 v163, s[42:43], 0, v163, s[50:51]
	v_cmp_gt_i32_e64 s[76:77], v19, v142
	v_addc_co_u32_e64 v156, s[42:43], 0, v156, s[72:73]
	v_cmp_gt_i32_e64 s[50:51], v19, v143
	v_addc_co_u32_e64 v157, s[42:43], 0, v157, s[74:75]
	v_cmp_gt_i32_e64 s[72:73], v19, v152
	v_addc_co_u32_e64 v158, s[42:43], 0, v158, s[76:77]
	v_cmp_gt_i32_e64 s[74:75], v19, v153
	v_addc_co_u32_e64 v159, s[42:43], 0, v159, s[50:51]
	v_cmp_gt_i32_e64 s[76:77], v19, v154
	v_addc_co_u32_e64 v160, s[42:43], 0, v160, s[72:73]
	v_cmp_gt_i32_e64 s[50:51], v19, v155
	v_addc_co_u32_e64 v161, s[42:43], 0, v161, s[74:75]
	v_cmp_gt_i32_e64 s[72:73], v20, v140
	v_addc_co_u32_e64 v162, s[42:43], 0, v162, s[76:77]
	v_cmp_gt_i32_e64 s[74:75], v20, v141
	v_addc_co_u32_e64 v163, s[42:43], 0, v163, s[50:51]
	v_cmp_gt_i32_e64 s[76:77], v20, v142
	v_addc_co_u32_e64 v156, s[42:43], 0, v156, s[72:73]
	v_cmp_gt_i32_e64 s[50:51], v20, v143
	v_addc_co_u32_e64 v157, s[42:43], 0, v157, s[74:75]
	v_cmp_gt_i32_e64 s[72:73], v20, v144
	v_addc_co_u32_e64 v158, s[42:43], 0, v158, s[76:77]
	v_cmp_gt_i32_e64 s[74:75], v20, v153
	v_addc_co_u32_e64 v159, s[42:43], 0, v159, s[50:51]
	v_cmp_gt_i32_e64 s[76:77], v20, v154
	v_addc_co_u32_e64 v160, s[42:43], 0, v160, s[72:73]
	v_cmp_gt_i32_e64 s[50:51], v20, v155
	v_addc_co_u32_e64 v161, s[42:43], 0, v161, s[74:75]
	v_cmp_gt_i32_e64 s[72:73], v21, v140
	v_addc_co_u32_e64 v162, s[42:43], 0, v162, s[76:77]
	v_cmp_gt_i32_e64 s[74:75], v21, v141
	v_addc_co_u32_e64 v163, s[42:43], 0, v163, s[50:51]
	v_cmp_gt_i32_e64 s[76:77], v21, v142
	v_addc_co_u32_e64 v156, s[42:43], 0, v156, s[72:73]
	v_cmp_gt_i32_e64 s[50:51], v21, v143
	v_addc_co_u32_e64 v157, s[42:43], 0, v157, s[74:75]
	v_cmp_gt_i32_e64 s[72:73], v21, v144
	v_addc_co_u32_e64 v158, s[42:43], 0, v158, s[76:77]
	v_cmp_gt_i32_e64 s[74:75], v21, v145
	v_addc_co_u32_e64 v159, s[42:43], 0, v159, s[50:51]
	v_cmp_gt_i32_e64 s[76:77], v21, v154
	v_addc_co_u32_e64 v160, s[42:43], 0, v160, s[72:73]
	v_cmp_gt_i32_e64 s[50:51], v21, v155
; DI void task_nsa(const P& p, int layer, int task, bf16_t* sm, int dm) {
;     ...
;     const float imp = cbuf[j * 65 + qq];
;     const bool valid = j <= cur;
;     const bool forced = (j == 0) || (j == cur) || (j == cur - 1);
;     const float score = valid ? imp + (forced ? 1e4f : 0.f) : -1e30f;
;     int rank = 0;
; #pragma unroll 4
;     for (int jp = 0; jp < 64; ++jp) {
;       const float sj = __int_as_float(__builtin_amdgcn_readlane(__float_as_int(score), jp));
;       rank += ((sj > score) || (sj == score && jp < j)) ? 1 : 0;
;     }
;     const unsigned long long mk = __ballot(rank < 16);
	v_addc_co_u32_e64 v161, s[42:43], 0, v161, s[74:75]
	v_cmp_gt_i32_e64 s[72:73], v22, v140
	v_addc_co_u32_e64 v162, s[42:43], 0, v162, s[76:77]
	v_cmp_gt_i32_e64 s[74:75], v22, v141
	v_addc_co_u32_e64 v163, s[42:43], 0, v163, s[50:51]
	v_cmp_gt_i32_e64 s[76:77], v22, v142
	v_addc_co_u32_e64 v156, s[42:43], 0, v156, s[72:73]
	v_cmp_gt_i32_e64 s[50:51], v22, v143
	v_addc_co_u32_e64 v157, s[42:43], 0, v157, s[74:75]
	v_cmp_gt_i32_e64 s[72:73], v22, v144
	v_addc_co_u32_e64 v158, s[42:43], 0, v158, s[76:77]
	v_cmp_gt_i32_e64 s[74:75], v22, v145
	v_addc_co_u32_e64 v159, s[42:43], 0, v159, s[50:51]
	v_cmp_gt_i32_e64 s[76:77], v22, v146
	v_addc_co_u32_e64 v160, s[42:43], 0, v160, s[72:73]
	v_cmp_gt_i32_e64 s[50:51], v22, v155
	v_addc_co_u32_e64 v161, s[42:43], 0, v161, s[74:75]
	v_cmp_gt_i32_e64 s[72:73], v23, v140
	v_addc_co_u32_e64 v162, s[42:43], 0, v162, s[76:77]
	v_cmp_gt_i32_e64 s[74:75], v23, v141
	v_addc_co_u32_e64 v163, s[42:43], 0, v163, s[50:51]
	v_cmp_gt_i32_e64 s[76:77], v23, v142
	v_addc_co_u32_e64 v156, s[42:43], 0, v156, s[72:73]
	v_cmp_gt_i32_e64 s[50:51], v23, v143
	v_addc_co_u32_e64 v157, s[42:43], 0, v157, s[74:75]
	v_cmp_gt_i32_e64 s[72:73], v23, v144
	v_addc_co_u32_e64 v158, s[42:43], 0, v158, s[76:77]
	v_cmp_gt_i32_e64 s[74:75], v23, v145
	v_addc_co_u32_e64 v159, s[42:43], 0, v159, s[50:51]
	v_cmp_gt_i32_e64 s[76:77], v23, v146
	v_addc_co_u32_e64 v160, s[42:43], 0, v160, s[72:73]
	v_cmp_gt_i32_e64 s[50:51], v23, v147
	v_addc_co_u32_e64 v161, s[42:43], 0, v161, s[74:75]
	v_addc_co_u32_e64 v162, s[42:43], 0, v162, s[76:77]
	v_addc_co_u32_e64 v163, s[42:43], 0, v163, s[50:51]
	s_cmp_gt_u32 8, s9
	s_cbranch_scc1 .Ltopk_oct_done
	ds_read_b32 v32, v171 offset:43328
	ds_read_b32 v33, v171 offset:43588
	ds_read_b32 v34, v171 offset:43848
	ds_read_b32 v35, v171 offset:44108
	ds_read_b32 v36, v171 offset:44368
	ds_read_b32 v37, v171 offset:44628
	ds_read_b32 v38, v171 offset:44888
	ds_read_b32 v39, v171 offset:45148
	s_cmp_lt_u32 1, s28
	s_cselect_b32 s31, 1, 0
	s_cmp_le_u32 1, s28
	s_cselect_b32 s32, 1, 0
	v_subrev_u32_e32 v140, s31, v116
	v_subrev_u32_e32 v141, s31, v117
	v_subrev_u32_e32 v142, s31, v118
	v_subrev_u32_e32 v143, s31, v119
	v_subrev_u32_e32 v144, s31, v120
	v_subrev_u32_e32 v145, s31, v121
	v_subrev_u32_e32 v146, s31, v122
	v_subrev_u32_e32 v147, s31, v123
	v_subrev_u32_e32 v148, s32, v116
	v_subrev_u32_e32 v149, s32, v117
	v_subrev_u32_e32 v150, s32, v118
	v_subrev_u32_e32 v151, s32, v119
	v_subrev_u32_e32 v152, s32, v120
	v_subrev_u32_e32 v153, s32, v121
	v_subrev_u32_e32 v154, s32, v122
	v_subrev_u32_e32 v155, s32, v123
	s_waitcnt lgkmcnt(8)
	v_cmp_gt_i32_e64 s[72:73], v24, v140
	v_cmp_gt_i32_e64 s[74:75], v24, v149
	v_cmp_gt_i32_e64 s[76:77], v24, v150
	v_addc_co_u32_e64 v156, s[42:43], 0, v156, s[72:73]
	v_cmp_gt_i32_e64 s[50:51], v24, v151
	v_addc_co_u32_e64 v157, s[42:43], 0, v157, s[74:75]
	v_cmp_gt_i32_e64 s[72:73], v24, v152
	v_addc_co_u32_e64 v158, s[42:43], 0, v158, s[76:77]
	v_cmp_gt_i32_e64 s[74:75], v24, v153
	v_addc_co_u32_e64 v159, s[42:43], 0, v159, s[50:51]
	v_cmp_gt_i32_e64 s[76:77], v24, v154
	v_addc_co_u32_e64 v160, s[42:43], 0, v160, s[72:73]
	v_cmp_gt_i32_e64 s[50:51], v24, v155
	v_addc_co_u32_e64 v161, s[42:43], 0, v161, s[74:75]
	v_cmp_gt_i32_e64 s[72:73], v25, v140
	v_addc_co_u32_e64 v162, s[42:43], 0, v162, s[76:77]
	v_cmp_gt_i32_e64 s[74:75], v25, v141
	v_addc_co_u32_e64 v163, s[42:43], 0, v163, s[50:51]
	v_cmp_gt_i32_e64 s[76:77], v25, v150
	v_addc_co_u32_e64 v156, s[42:43], 0, v156, s[72:73]
	v_cmp_gt_i32_e64 s[50:51], v25, v151
	v_addc_co_u32_e64 v157, s[42:43], 0, v157, s[74:75]
	v_cmp_gt_i32_e64 s[72:73], v25, v152
	v_addc_co_u32_e64 v158, s[42:43], 0, v158, s[76:77]
	v_cmp_gt_i32_e64 s[74:75], v25, v153
	v_addc_co_u32_e64 v159, s[42:43], 0, v159, s[50:51]
	v_cmp_gt_i32_e64 s[76:77], v25, v154
	v_addc_co_u32_e64 v160, s[42:43], 0, v160, s[72:73]
	v_cmp_gt_i32_e64 s[50:51], v25, v155
	v_addc_co_u32_e64 v161, s[42:43], 0, v161, s[74:75]
	v_cmp_gt_i32_e64 s[72:73], v26, v140
	v_addc_co_u32_e64 v162, s[42:43], 0, v162, s[76:77]
	v_cmp_gt_i32_e64 s[74:75], v26, v141
	v_addc_co_u32_e64 v163, s[42:43], 0, v163, s[50:51]
	v_cmp_gt_i32_e64 s[76:77], v26, v142
	v_addc_co_u32_e64 v156, s[42:43], 0, v156, s[72:73]
	v_cmp_gt_i32_e64 s[50:51], v26, v151
	v_addc_co_u32_e64 v157, s[42:43], 0, v157, s[74:75]
	v_cmp_gt_i32_e64 s[72:73], v26, v152
	v_addc_co_u32_e64 v158, s[42:43], 0, v158, s[76:77]
	v_cmp_gt_i32_e64 s[74:75], v26, v153
	v_addc_co_u32_e64 v159, s[42:43], 0, v159, s[50:51]
	v_cmp_gt_i32_e64 s[76:77], v26, v154
	v_addc_co_u32_e64 v160, s[42:43], 0, v160, s[72:73]
	v_cmp_gt_i32_e64 s[50:51], v26, v155
	v_addc_co_u32_e64 v161, s[42:43], 0, v161, s[74:75]
	v_cmp_gt_i32_e64 s[72:73], v27, v140
	v_addc_co_u32_e64 v162, s[42:43], 0, v162, s[76:77]
	v_cmp_gt_i32_e64 s[74:75], v27, v141
	v_addc_co_u32_e64 v163, s[42:43], 0, v163, s[50:51]
	v_cmp_gt_i32_e64 s[76:77], v27, v142
	v_addc_co_u32_e64 v156, s[42:43], 0, v156, s[72:73]
	v_cmp_gt_i32_e64 s[50:51], v27, v143
	v_addc_co_u32_e64 v157, s[42:43], 0, v157, s[74:75]
	v_cmp_gt_i32_e64 s[72:73], v27, v152
	v_addc_co_u32_e64 v158, s[42:43], 0, v158, s[76:77]
	v_cmp_gt_i32_e64 s[74:75], v27, v153
	v_addc_co_u32_e64 v159, s[42:43], 0, v159, s[50:51]
	v_cmp_gt_i32_e64 s[76:77], v27, v154
	v_addc_co_u32_e64 v160, s[42:43], 0, v160, s[72:73]
	v_cmp_gt_i32_e64 s[50:51], v27, v155
	v_addc_co_u32_e64 v161, s[42:43], 0, v161, s[74:75]
	v_cmp_gt_i32_e64 s[72:73], v28, v140
	v_addc_co_u32_e64 v162, s[42:43], 0, v162, s[76:77]
	v_cmp_gt_i32_e64 s[74:75], v28, v141
	v_addc_co_u32_e64 v163, s[42:43], 0, v163, s[50:51]
	v_cmp_gt_i32_e64 s[76:77], v28, v142
; DI void task_nsa(const P& p, int layer, int task, bf16_t* sm, int dm) {
;     ...
;     const float imp = cbuf[j * 65 + qq];
;     const bool valid = j <= cur;
;     const bool forced = (j == 0) || (j == cur) || (j == cur - 1);
;     const float score = valid ? imp + (forced ? 1e4f : 0.f) : -1e30f;
;     int rank = 0;
; #pragma unroll 4
;     for (int jp = 0; jp < 64; ++jp) {
;       const float sj = __int_as_float(__builtin_amdgcn_readlane(__float_as_int(score), jp));
;       rank += ((sj > score) || (sj == score && jp < j)) ? 1 : 0;
;     }
;     const unsigned long long mk = __ballot(rank < 16);
	v_addc_co_u32_e64 v156, s[42:43], 0, v156, s[72:73]
	v_cmp_gt_i32_e64 s[50:51], v28, v143
	v_addc_co_u32_e64 v157, s[42:43], 0, v157, s[74:75]
	v_cmp_gt_i32_e64 s[72:73], v28, v144
	v_addc_co_u32_e64 v158, s[42:43], 0, v158, s[76:77]
	v_cmp_gt_i32_e64 s[74:75], v28, v153
	v_addc_co_u32_e64 v159, s[42:43], 0, v159, s[50:51]
	v_cmp_gt_i32_e64 s[76:77], v28, v154
	v_addc_co_u32_e64 v160, s[42:43], 0, v160, s[72:73]
	v_cmp_gt_i32_e64 s[50:51], v28, v155
	v_addc_co_u32_e64 v161, s[42:43], 0, v161, s[74:75]
	v_cmp_gt_i32_e64 s[72:73], v29, v140
	v_addc_co_u32_e64 v162, s[42:43], 0, v162, s[76:77]
	v_cmp_gt_i32_e64 s[74:75], v29, v141
	v_addc_co_u32_e64 v163, s[42:43], 0, v163, s[50:51]
	v_cmp_gt_i32_e64 s[76:77], v29, v142
	v_addc_co_u32_e64 v156, s[42:43], 0, v156, s[72:73]
	v_cmp_gt_i32_e64 s[50:51], v29, v143
	v_addc_co_u32_e64 v157, s[42:43], 0, v157, s[74:75]
	v_cmp_gt_i32_e64 s[72:73], v29, v144
	v_addc_co_u32_e64 v158, s[42:43], 0, v158, s[76:77]
	v_cmp_gt_i32_e64 s[74:75], v29, v145
	v_addc_co_u32_e64 v159, s[42:43], 0, v159, s[50:51]
	v_cmp_gt_i32_e64 s[76:77], v29, v154
	v_addc_co_u32_e64 v160, s[42:43], 0, v160, s[72:73]
	v_cmp_gt_i32_e64 s[50:51], v29, v155
	v_addc_co_u32_e64 v161, s[42:43], 0, v161, s[74:75]
	v_cmp_gt_i32_e64 s[72:73], v30, v140
	v_addc_co_u32_e64 v162, s[42:43], 0, v162, s[76:77]
	v_cmp_gt_i32_e64 s[74:75], v30, v141
	v_addc_co_u32_e64 v163, s[42:43], 0, v163, s[50:51]
	v_cmp_gt_i32_e64 s[76:77], v30, v142
	v_addc_co_u32_e64 v156, s[42:43], 0, v156, s[72:73]
	v_cmp_gt_i32_e64 s[50:51], v30, v143
	v_addc_co_u32_e64 v157, s[42:43], 0, v157, s[74:75]
	v_cmp_gt_i32_e64 s[72:73], v30, v144
	v_addc_co_u32_e64 v158, s[42:43], 0, v158, s[76:77]
	v_cmp_gt_i32_e64 s[74:75], v30, v145
	v_addc_co_u32_e64 v159, s[42:43], 0, v159, s[50:51]
	v_cmp_gt_i32_e64 s[76:77], v30, v146
	v_addc_co_u32_e64 v160, s[42:43], 0, v160, s[72:73]
	v_cmp_gt_i32_e64 s[50:51], v30, v155
	v_addc_co_u32_e64 v161, s[42:43], 0, v161, s[74:75]
	v_cmp_gt_i32_e64 s[72:73], v31, v140
	v_addc_co_u32_e64 v162, s[42:43], 0, v162, s[76:77]
	v_cmp_gt_i32_e64 s[74:75], v31, v141
	v_addc_co_u32_e64 v163, s[42:43], 0, v163, s[50:51]
	v_cmp_gt_i32_e64 s[76:77], v31, v142
	v_addc_co_u32_e64 v156, s[42:43], 0, v156, s[72:73]
	v_cmp_gt_i32_e64 s[50:51], v31, v143
	v_addc_co_u32_e64 v157, s[42:43], 0, v157, s[74:75]
	v_cmp_gt_i32_e64 s[72:73], v31, v144
	v_addc_co_u32_e64 v158, s[42:43], 0, v158, s[76:77]
	v_cmp_gt_i32_e64 s[74:75], v31, v145
	v_addc_co_u32_e64 v159, s[42:43], 0, v159, s[50:51]
	v_cmp_gt_i32_e64 s[76:77], v31, v146
	v_addc_co_u32_e64 v160, s[42:43], 0, v160, s[72:73]
	v_cmp_gt_i32_e64 s[50:51], v31, v147
	v_addc_co_u32_e64 v161, s[42:43], 0, v161, s[74:75]
	v_addc_co_u32_e64 v162, s[42:43], 0, v162, s[76:77]
	v_addc_co_u32_e64 v163, s[42:43], 0, v163, s[50:51]
	s_cmp_gt_u32 16, s9
	s_cbranch_scc1 .Ltopk_oct_done
	ds_read_b32 v40, v171 offset:45408
	ds_read_b32 v41, v171 offset:45668
	ds_read_b32 v42, v171 offset:45928
	ds_read_b32 v43, v171 offset:46188
	ds_read_b32 v44, v171 offset:46448
	ds_read_b32 v45, v171 offset:46708
	ds_read_b32 v46, v171 offset:46968
	ds_read_b32 v47, v171 offset:47228
	s_cmp_lt_u32 2, s28
	s_cselect_b32 s31, 1, 0
	s_cmp_le_u32 2, s28
	s_cselect_b32 s32, 1, 0
	v_subrev_u32_e32 v140, s31, v116
	v_subrev_u32_e32 v141, s31, v117
	v_subrev_u32_e32 v142, s31, v118
	v_subrev_u32_e32 v143, s31, v119
	v_subrev_u32_e32 v144, s31, v120
	v_subrev_u32_e32 v145, s31, v121
	v_subrev_u32_e32 v146, s31, v122
	v_subrev_u32_e32 v147, s31, v123
	v_subrev_u32_e32 v148, s32, v116
	v_subrev_u32_e32 v149, s32, v117
	v_subrev_u32_e32 v150, s32, v118
	v_subrev_u32_e32 v151, s32, v119
	v_subrev_u32_e32 v152, s32, v120
	v_subrev_u32_e32 v153, s32, v121
	v_subrev_u32_e32 v154, s32, v122
	v_subrev_u32_e32 v155, s32, v123
	s_waitcnt lgkmcnt(8)
	v_cmp_gt_i32_e64 s[72:73], v32, v140
	v_cmp_gt_i32_e64 s[74:75], v32, v149
	v_cmp_gt_i32_e64 s[76:77], v32, v150
	v_addc_co_u32_e64 v156, s[42:43], 0, v156, s[72:73]
	v_cmp_gt_i32_e64 s[50:51], v32, v151
	v_addc_co_u32_e64 v157, s[42:43], 0, v157, s[74:75]
	v_cmp_gt_i32_e64 s[72:73], v32, v152
	v_addc_co_u32_e64 v158, s[42:43], 0, v158, s[76:77]
	v_cmp_gt_i32_e64 s[74:75], v32, v153
	v_addc_co_u32_e64 v159, s[42:43], 0, v159, s[50:51]
	v_cmp_gt_i32_e64 s[76:77], v32, v154
	v_addc_co_u32_e64 v160, s[42:43], 0, v160, s[72:73]
	v_cmp_gt_i32_e64 s[50:51], v32, v155
	v_addc_co_u32_e64 v161, s[42:43], 0, v161, s[74:75]
	v_cmp_gt_i32_e64 s[72:73], v33, v140
	v_addc_co_u32_e64 v162, s[42:43], 0, v162, s[76:77]
	v_cmp_gt_i32_e64 s[74:75], v33, v141
	v_addc_co_u32_e64 v163, s[42:43], 0, v163, s[50:51]
	v_cmp_gt_i32_e64 s[76:77], v33, v150
	v_addc_co_u32_e64 v156, s[42:43], 0, v156, s[72:73]
	v_cmp_gt_i32_e64 s[50:51], v33, v151
	v_addc_co_u32_e64 v157, s[42:43], 0, v157, s[74:75]
	v_cmp_gt_i32_e64 s[72:73], v33, v152
	v_addc_co_u32_e64 v158, s[42:43], 0, v158, s[76:77]
	v_cmp_gt_i32_e64 s[74:75], v33, v153
	v_addc_co_u32_e64 v159, s[42:43], 0, v159, s[50:51]
	v_cmp_gt_i32_e64 s[76:77], v33, v154
	v_addc_co_u32_e64 v160, s[42:43], 0, v160, s[72:73]
	v_cmp_gt_i32_e64 s[50:51], v33, v155
	v_addc_co_u32_e64 v161, s[42:43], 0, v161, s[74:75]
	v_cmp_gt_i32_e64 s[72:73], v34, v140
	v_addc_co_u32_e64 v162, s[42:43], 0, v162, s[76:77]
	v_cmp_gt_i32_e64 s[74:75], v34, v141
	v_addc_co_u32_e64 v163, s[42:43], 0, v163, s[50:51]
	v_cmp_gt_i32_e64 s[76:77], v34, v142
	v_addc_co_u32_e64 v156, s[42:43], 0, v156, s[72:73]
	v_cmp_gt_i32_e64 s[50:51], v34, v151
	v_addc_co_u32_e64 v157, s[42:43], 0, v157, s[74:75]
	v_cmp_gt_i32_e64 s[72:73], v34, v152
	v_addc_co_u32_e64 v158, s[42:43], 0, v158, s[76:77]
	v_cmp_gt_i32_e64 s[74:75], v34, v153
; DI void task_nsa(const P& p, int layer, int task, bf16_t* sm, int dm) {
;     ...
;     const float imp = cbuf[j * 65 + qq];
;     const bool valid = j <= cur;
;     const bool forced = (j == 0) || (j == cur) || (j == cur - 1);
;     const float score = valid ? imp + (forced ? 1e4f : 0.f) : -1e30f;
;     int rank = 0;
; #pragma unroll 4
;     for (int jp = 0; jp < 64; ++jp) {
;       const float sj = __int_as_float(__builtin_amdgcn_readlane(__float_as_int(score), jp));
;       rank += ((sj > score) || (sj == score && jp < j)) ? 1 : 0;
;     }
;     const unsigned long long mk = __ballot(rank < 16);
	v_addc_co_u32_e64 v159, s[42:43], 0, v159, s[50:51]
	v_cmp_gt_i32_e64 s[76:77], v34, v154
	v_addc_co_u32_e64 v160, s[42:43], 0, v160, s[72:73]
	v_cmp_gt_i32_e64 s[50:51], v34, v155
	v_addc_co_u32_e64 v161, s[42:43], 0, v161, s[74:75]
	v_cmp_gt_i32_e64 s[72:73], v35, v140
	v_addc_co_u32_e64 v162, s[42:43], 0, v162, s[76:77]
	v_cmp_gt_i32_e64 s[74:75], v35, v141
	v_addc_co_u32_e64 v163, s[42:43], 0, v163, s[50:51]
	v_cmp_gt_i32_e64 s[76:77], v35, v142
	v_addc_co_u32_e64 v156, s[42:43], 0, v156, s[72:73]
	v_cmp_gt_i32_e64 s[50:51], v35, v143
	v_addc_co_u32_e64 v157, s[42:43], 0, v157, s[74:75]
	v_cmp_gt_i32_e64 s[72:73], v35, v152
	v_addc_co_u32_e64 v158, s[42:43], 0, v158, s[76:77]
	v_cmp_gt_i32_e64 s[74:75], v35, v153
	v_addc_co_u32_e64 v159, s[42:43], 0, v159, s[50:51]
	v_cmp_gt_i32_e64 s[76:77], v35, v154
	v_addc_co_u32_e64 v160, s[42:43], 0, v160, s[72:73]
	v_cmp_gt_i32_e64 s[50:51], v35, v155
	v_addc_co_u32_e64 v161, s[42:43], 0, v161, s[74:75]
	v_cmp_gt_i32_e64 s[72:73], v36, v140
	v_addc_co_u32_e64 v162, s[42:43], 0, v162, s[76:77]
	v_cmp_gt_i32_e64 s[74:75], v36, v141
	v_addc_co_u32_e64 v163, s[42:43], 0, v163, s[50:51]
	v_cmp_gt_i32_e64 s[76:77], v36, v142
	v_addc_co_u32_e64 v156, s[42:43], 0, v156, s[72:73]
	v_cmp_gt_i32_e64 s[50:51], v36, v143
	v_addc_co_u32_e64 v157, s[42:43], 0, v157, s[74:75]
	v_cmp_gt_i32_e64 s[72:73], v36, v144
	v_addc_co_u32_e64 v158, s[42:43], 0, v158, s[76:77]
	v_cmp_gt_i32_e64 s[74:75], v36, v153
	v_addc_co_u32_e64 v159, s[42:43], 0, v159, s[50:51]
	v_cmp_gt_i32_e64 s[76:77], v36, v154
	v_addc_co_u32_e64 v160, s[42:43], 0, v160, s[72:73]
	v_cmp_gt_i32_e64 s[50:51], v36, v155
	v_addc_co_u32_e64 v161, s[42:43], 0, v161, s[74:75]
	v_cmp_gt_i32_e64 s[72:73], v37, v140
	v_addc_co_u32_e64 v162, s[42:43], 0, v162, s[76:77]
	v_cmp_gt_i32_e64 s[74:75], v37, v141
	v_addc_co_u32_e64 v163, s[42:43], 0, v163, s[50:51]
	v_cmp_gt_i32_e64 s[76:77], v37, v142
	v_addc_co_u32_e64 v156, s[42:43], 0, v156, s[72:73]
	v_cmp_gt_i32_e64 s[50:51], v37, v143
	v_addc_co_u32_e64 v157, s[42:43], 0, v157, s[74:75]
	v_cmp_gt_i32_e64 s[72:73], v37, v144
	v_addc_co_u32_e64 v158, s[42:43], 0, v158, s[76:77]
	v_cmp_gt_i32_e64 s[74:75], v37, v145
	v_addc_co_u32_e64 v159, s[42:43], 0, v159, s[50:51]
	v_cmp_gt_i32_e64 s[76:77], v37, v154
	v_addc_co_u32_e64 v160, s[42:43], 0, v160, s[72:73]
	v_cmp_gt_i32_e64 s[50:51], v37, v155
	v_addc_co_u32_e64 v161, s[42:43], 0, v161, s[74:75]
	v_cmp_gt_i32_e64 s[72:73], v38, v140
	v_addc_co_u32_e64 v162, s[42:43], 0, v162, s[76:77]
	v_cmp_gt_i32_e64 s[74:75], v38, v141
	v_addc_co_u32_e64 v163, s[42:43], 0, v163, s[50:51]
	v_cmp_gt_i32_e64 s[76:77], v38, v142
	v_addc_co_u32_e64 v156, s[42:43], 0, v156, s[72:73]
	v_cmp_gt_i32_e64 s[50:51], v38, v143
	v_addc_co_u32_e64 v157, s[42:43], 0, v157, s[74:75]
	v_cmp_gt_i32_e64 s[72:73], v38, v144
	v_addc_co_u32_e64 v158, s[42:43], 0, v158, s[76:77]
	v_cmp_gt_i32_e64 s[74:75], v38, v145
	v_addc_co_u32_e64 v159, s[42:43], 0, v159, s[50:51]
	v_cmp_gt_i32_e64 s[76:77], v38, v146
	v_addc_co_u32_e64 v160, s[42:43], 0, v160, s[72:73]
	v_cmp_gt_i32_e64 s[50:51], v38, v155
	v_addc_co_u32_e64 v161, s[42:43], 0, v161, s[74:75]
	v_cmp_gt_i32_e64 s[72:73], v39, v140
	v_addc_co_u32_e64 v162, s[42:43], 0, v162, s[76:77]
	v_cmp_gt_i32_e64 s[74:75], v39, v141
	v_addc_co_u32_e64 v163, s[42:43], 0, v163, s[50:51]
	v_cmp_gt_i32_e64 s[76:77], v39, v142
	v_addc_co_u32_e64 v156, s[42:43], 0, v156, s[72:73]
	v_cmp_gt_i32_e64 s[50:51], v39, v143
	v_addc_co_u32_e64 v157, s[42:43], 0, v157, s[74:75]
	v_cmp_gt_i32_e64 s[72:73], v39, v144
	v_addc_co_u32_e64 v158, s[42:43], 0, v158, s[76:77]
	v_cmp_gt_i32_e64 s[74:75], v39, v145
	v_addc_co_u32_e64 v159, s[42:43], 0, v159, s[50:51]
	v_cmp_gt_i32_e64 s[76:77], v39, v146
	v_addc_co_u32_e64 v160, s[42:43], 0, v160, s[72:73]
	v_cmp_gt_i32_e64 s[50:51], v39, v147
	v_addc_co_u32_e64 v161, s[42:43], 0, v161, s[74:75]
	v_addc_co_u32_e64 v162, s[42:43], 0, v162, s[76:77]
	v_addc_co_u32_e64 v163, s[42:43], 0, v163, s[50:51]
	s_cmp_gt_u32 24, s9
	s_cbranch_scc1 .Ltopk_oct_done
	ds_read_b32 v48, v171 offset:47488
	ds_read_b32 v49, v171 offset:47748
	ds_read_b32 v50, v171 offset:48008
	ds_read_b32 v51, v171 offset:48268
	ds_read_b32 v52, v171 offset:48528
	ds_read_b32 v53, v171 offset:48788
	ds_read_b32 v54, v171 offset:49048
	ds_read_b32 v55, v171 offset:49308
	s_cmp_lt_u32 3, s28
	s_cselect_b32 s31, 1, 0
	s_cmp_le_u32 3, s28
	s_cselect_b32 s32, 1, 0
	v_subrev_u32_e32 v140, s31, v116
	v_subrev_u32_e32 v141, s31, v117
	v_subrev_u32_e32 v142, s31, v118
	v_subrev_u32_e32 v143, s31, v119
	v_subrev_u32_e32 v144, s31, v120
	v_subrev_u32_e32 v145, s31, v121
	v_subrev_u32_e32 v146, s31, v122
	v_subrev_u32_e32 v147, s31, v123
	v_subrev_u32_e32 v148, s32, v116
	v_subrev_u32_e32 v149, s32, v117
	v_subrev_u32_e32 v150, s32, v118
	v_subrev_u32_e32 v151, s32, v119
	v_subrev_u32_e32 v152, s32, v120
	v_subrev_u32_e32 v153, s32, v121
	v_subrev_u32_e32 v154, s32, v122
	v_subrev_u32_e32 v155, s32, v123
	s_waitcnt lgkmcnt(8)
; DI void task_nsa(const P& p, int layer, int task, bf16_t* sm, int dm) {
;     ...
;     const float imp = cbuf[j * 65 + qq];
;     const bool valid = j <= cur;
;     const bool forced = (j == 0) || (j == cur) || (j == cur - 1);
;     const float score = valid ? imp + (forced ? 1e4f : 0.f) : -1e30f;
;     int rank = 0;
; #pragma unroll 4
;     for (int jp = 0; jp < 64; ++jp) {
;       const float sj = __int_as_float(__builtin_amdgcn_readlane(__float_as_int(score), jp));
;       rank += ((sj > score) || (sj == score && jp < j)) ? 1 : 0;
;     }
;     const unsigned long long mk = __ballot(rank < 16);
	v_cmp_gt_i32_e64 s[72:73], v40, v140
	v_cmp_gt_i32_e64 s[74:75], v40, v149
	v_cmp_gt_i32_e64 s[76:77], v40, v150
	v_addc_co_u32_e64 v156, s[42:43], 0, v156, s[72:73]
	v_cmp_gt_i32_e64 s[50:51], v40, v151
	v_addc_co_u32_e64 v157, s[42:43], 0, v157, s[74:75]
	v_cmp_gt_i32_e64 s[72:73], v40, v152
	v_addc_co_u32_e64 v158, s[42:43], 0, v158, s[76:77]
	v_cmp_gt_i32_e64 s[74:75], v40, v153
	v_addc_co_u32_e64 v159, s[42:43], 0, v159, s[50:51]
	v_cmp_gt_i32_e64 s[76:77], v40, v154
	v_addc_co_u32_e64 v160, s[42:43], 0, v160, s[72:73]
	v_cmp_gt_i32_e64 s[50:51], v40, v155
	v_addc_co_u32_e64 v161, s[42:43], 0, v161, s[74:75]
	v_cmp_gt_i32_e64 s[72:73], v41, v140
	v_addc_co_u32_e64 v162, s[42:43], 0, v162, s[76:77]
	v_cmp_gt_i32_e64 s[74:75], v41, v141
	v_addc_co_u32_e64 v163, s[42:43], 0, v163, s[50:51]
	v_cmp_gt_i32_e64 s[76:77], v41, v150
	v_addc_co_u32_e64 v156, s[42:43], 0, v156, s[72:73]
	v_cmp_gt_i32_e64 s[50:51], v41, v151
	v_addc_co_u32_e64 v157, s[42:43], 0, v157, s[74:75]
	v_cmp_gt_i32_e64 s[72:73], v41, v152
	v_addc_co_u32_e64 v158, s[42:43], 0, v158, s[76:77]
	v_cmp_gt_i32_e64 s[74:75], v41, v153
	v_addc_co_u32_e64 v159, s[42:43], 0, v159, s[50:51]
	v_cmp_gt_i32_e64 s[76:77], v41, v154
	v_addc_co_u32_e64 v160, s[42:43], 0, v160, s[72:73]
	v_cmp_gt_i32_e64 s[50:51], v41, v155
	v_addc_co_u32_e64 v161, s[42:43], 0, v161, s[74:75]
	v_cmp_gt_i32_e64 s[72:73], v42, v140
	v_addc_co_u32_e64 v162, s[42:43], 0, v162, s[76:77]
	v_cmp_gt_i32_e64 s[74:75], v42, v141
	v_addc_co_u32_e64 v163, s[42:43], 0, v163, s[50:51]
	v_cmp_gt_i32_e64 s[76:77], v42, v142
	v_addc_co_u32_e64 v156, s[42:43], 0, v156, s[72:73]
	v_cmp_gt_i32_e64 s[50:51], v42, v151
	v_addc_co_u32_e64 v157, s[42:43], 0, v157, s[74:75]
	v_cmp_gt_i32_e64 s[72:73], v42, v152
	v_addc_co_u32_e64 v158, s[42:43], 0, v158, s[76:77]
	v_cmp_gt_i32_e64 s[74:75], v42, v153
	v_addc_co_u32_e64 v159, s[42:43], 0, v159, s[50:51]
	v_cmp_gt_i32_e64 s[76:77], v42, v154
	v_addc_co_u32_e64 v160, s[42:43], 0, v160, s[72:73]
	v_cmp_gt_i32_e64 s[50:51], v42, v155
	v_addc_co_u32_e64 v161, s[42:43], 0, v161, s[74:75]
	v_cmp_gt_i32_e64 s[72:73], v43, v140
	v_addc_co_u32_e64 v162, s[42:43], 0, v162, s[76:77]
	v_cmp_gt_i32_e64 s[74:75], v43, v141
	v_addc_co_u32_e64 v163, s[42:43], 0, v163, s[50:51]
	v_cmp_gt_i32_e64 s[76:77], v43, v142
	v_addc_co_u32_e64 v156, s[42:43], 0, v156, s[72:73]
	v_cmp_gt_i32_e64 s[50:51], v43, v143
	v_addc_co_u32_e64 v157, s[42:43], 0, v157, s[74:75]
	v_cmp_gt_i32_e64 s[72:73], v43, v152
	v_addc_co_u32_e64 v158, s[42:43], 0, v158, s[76:77]
	v_cmp_gt_i32_e64 s[74:75], v43, v153
	v_addc_co_u32_e64 v159, s[42:43], 0, v159, s[50:51]
	v_cmp_gt_i32_e64 s[76:77], v43, v154
	v_addc_co_u32_e64 v160, s[42:43], 0, v160, s[72:73]
	v_cmp_gt_i32_e64 s[50:51], v43, v155
	v_addc_co_u32_e64 v161, s[42:43], 0, v161, s[74:75]
	v_cmp_gt_i32_e64 s[72:73], v44, v140
	v_addc_co_u32_e64 v162, s[42:43], 0, v162, s[76:77]
	v_cmp_gt_i32_e64 s[74:75], v44, v141
	v_addc_co_u32_e64 v163, s[42:43], 0, v163, s[50:51]
	v_cmp_gt_i32_e64 s[76:77], v44, v142
	v_addc_co_u32_e64 v156, s[42:43], 0, v156, s[72:73]
	v_cmp_gt_i32_e64 s[50:51], v44, v143
	v_addc_co_u32_e64 v157, s[42:43], 0, v157, s[74:75]
	v_cmp_gt_i32_e64 s[72:73], v44, v144
	v_addc_co_u32_e64 v158, s[42:43], 0, v158, s[76:77]
	v_cmp_gt_i32_e64 s[74:75], v44, v153
	v_addc_co_u32_e64 v159, s[42:43], 0, v159, s[50:51]
	v_cmp_gt_i32_e64 s[76:77], v44, v154
	v_addc_co_u32_e64 v160, s[42:43], 0, v160, s[72:73]
	v_cmp_gt_i32_e64 s[50:51], v44, v155
	v_addc_co_u32_e64 v161, s[42:43], 0, v161, s[74:75]
	v_cmp_gt_i32_e64 s[72:73], v45, v140
	v_addc_co_u32_e64 v162, s[42:43], 0, v162, s[76:77]
	v_cmp_gt_i32_e64 s[74:75], v45, v141
	v_addc_co_u32_e64 v163, s[42:43], 0, v163, s[50:51]
	v_cmp_gt_i32_e64 s[76:77], v45, v142
	v_addc_co_u32_e64 v156, s[42:43], 0, v156, s[72:73]
	v_cmp_gt_i32_e64 s[50:51], v45, v143
	v_addc_co_u32_e64 v157, s[42:43], 0, v157, s[74:75]
	v_cmp_gt_i32_e64 s[72:73], v45, v144
	v_addc_co_u32_e64 v158, s[42:43], 0, v158, s[76:77]
	v_cmp_gt_i32_e64 s[74:75], v45, v145
	v_addc_co_u32_e64 v159, s[42:43], 0, v159, s[50:51]
	v_cmp_gt_i32_e64 s[76:77], v45, v154
	v_addc_co_u32_e64 v160, s[42:43], 0, v160, s[72:73]
	v_cmp_gt_i32_e64 s[50:51], v45, v155
	v_addc_co_u32_e64 v161, s[42:43], 0, v161, s[74:75]
	v_cmp_gt_i32_e64 s[72:73], v46, v140
	v_addc_co_u32_e64 v162, s[42:43], 0, v162, s[76:77]
	v_cmp_gt_i32_e64 s[74:75], v46, v141
	v_addc_co_u32_e64 v163, s[42:43], 0, v163, s[50:51]
	v_cmp_gt_i32_e64 s[76:77], v46, v142
	v_addc_co_u32_e64 v156, s[42:43], 0, v156, s[72:73]
	v_cmp_gt_i32_e64 s[50:51], v46, v143
	v_addc_co_u32_e64 v157, s[42:43], 0, v157, s[74:75]
	v_cmp_gt_i32_e64 s[72:73], v46, v144
	v_addc_co_u32_e64 v158, s[42:43], 0, v158, s[76:77]
	v_cmp_gt_i32_e64 s[74:75], v46, v145
	v_addc_co_u32_e64 v159, s[42:43], 0, v159, s[50:51]
	v_cmp_gt_i32_e64 s[76:77], v46, v146
	v_addc_co_u32_e64 v160, s[42:43], 0, v160, s[72:73]
	v_cmp_gt_i32_e64 s[50:51], v46, v155
	v_addc_co_u32_e64 v161, s[42:43], 0, v161, s[74:75]
	v_cmp_gt_i32_e64 s[72:73], v47, v140
	v_addc_co_u32_e64 v162, s[42:43], 0, v162, s[76:77]
	v_cmp_gt_i32_e64 s[74:75], v47, v141
	v_addc_co_u32_e64 v163, s[42:43], 0, v163, s[50:51]
	v_cmp_gt_i32_e64 s[76:77], v47, v142
	v_addc_co_u32_e64 v156, s[42:43], 0, v156, s[72:73]
	v_cmp_gt_i32_e64 s[50:51], v47, v143
	v_addc_co_u32_e64 v157, s[42:43], 0, v157, s[74:75]
	v_cmp_gt_i32_e64 s[72:73], v47, v144
	v_addc_co_u32_e64 v158, s[42:43], 0, v158, s[76:77]
	v_cmp_gt_i32_e64 s[74:75], v47, v145
	v_addc_co_u32_e64 v159, s[42:43], 0, v159, s[50:51]
	v_cmp_gt_i32_e64 s[76:77], v47, v146
	v_addc_co_u32_e64 v160, s[42:43], 0, v160, s[72:73]
	v_cmp_gt_i32_e64 s[50:51], v47, v147
	v_addc_co_u32_e64 v161, s[42:43], 0, v161, s[74:75]
	v_addc_co_u32_e64 v162, s[42:43], 0, v162, s[76:77]
	v_addc_co_u32_e64 v163, s[42:43], 0, v163, s[50:51]
	s_cmp_gt_u32 32, s9
	s_cbranch_scc1 .Ltopk_oct_done
; DI void task_nsa(const P& p, int layer, int task, bf16_t* sm, int dm) {
;     ...
;     const float imp = cbuf[j * 65 + qq];
;     const bool valid = j <= cur;
;     const bool forced = (j == 0) || (j == cur) || (j == cur - 1);
;     const float score = valid ? imp + (forced ? 1e4f : 0.f) : -1e30f;
;     int rank = 0;
; #pragma unroll 4
;     for (int jp = 0; jp < 64; ++jp) {
;       const float sj = __int_as_float(__builtin_amdgcn_readlane(__float_as_int(score), jp));
;       rank += ((sj > score) || (sj == score && jp < j)) ? 1 : 0;
;     }
;     const unsigned long long mk = __ballot(rank < 16);
	ds_read_b32 v56, v171 offset:49568
	ds_read_b32 v57, v171 offset:49828
	ds_read_b32 v58, v171 offset:50088
	ds_read_b32 v59, v171 offset:50348
	ds_read_b32 v60, v171 offset:50608
	ds_read_b32 v61, v171 offset:50868
	ds_read_b32 v62, v171 offset:51128
	ds_read_b32 v63, v171 offset:51388
	s_cmp_lt_u32 4, s28
	s_cselect_b32 s31, 1, 0
	s_cmp_le_u32 4, s28
	s_cselect_b32 s32, 1, 0
	v_subrev_u32_e32 v140, s31, v116
	v_subrev_u32_e32 v141, s31, v117
	v_subrev_u32_e32 v142, s31, v118
	v_subrev_u32_e32 v143, s31, v119
	v_subrev_u32_e32 v144, s31, v120
	v_subrev_u32_e32 v145, s31, v121
	v_subrev_u32_e32 v146, s31, v122
	v_subrev_u32_e32 v147, s31, v123
	v_subrev_u32_e32 v148, s32, v116
	v_subrev_u32_e32 v149, s32, v117
	v_subrev_u32_e32 v150, s32, v118
	v_subrev_u32_e32 v151, s32, v119
	v_subrev_u32_e32 v152, s32, v120
	v_subrev_u32_e32 v153, s32, v121
	v_subrev_u32_e32 v154, s32, v122
	v_subrev_u32_e32 v155, s32, v123
	s_waitcnt lgkmcnt(8)
	v_cmp_gt_i32_e64 s[72:73], v48, v140
	v_cmp_gt_i32_e64 s[74:75], v48, v149
	v_cmp_gt_i32_e64 s[76:77], v48, v150
	v_addc_co_u32_e64 v156, s[42:43], 0, v156, s[72:73]
	v_cmp_gt_i32_e64 s[50:51], v48, v151
	v_addc_co_u32_e64 v157, s[42:43], 0, v157, s[74:75]
	v_cmp_gt_i32_e64 s[72:73], v48, v152
	v_addc_co_u32_e64 v158, s[42:43], 0, v158, s[76:77]
	v_cmp_gt_i32_e64 s[74:75], v48, v153
	v_addc_co_u32_e64 v159, s[42:43], 0, v159, s[50:51]
	v_cmp_gt_i32_e64 s[76:77], v48, v154
	v_addc_co_u32_e64 v160, s[42:43], 0, v160, s[72:73]
	v_cmp_gt_i32_e64 s[50:51], v48, v155
	v_addc_co_u32_e64 v161, s[42:43], 0, v161, s[74:75]
	v_cmp_gt_i32_e64 s[72:73], v49, v140
	v_addc_co_u32_e64 v162, s[42:43], 0, v162, s[76:77]
	v_cmp_gt_i32_e64 s[74:75], v49, v141
	v_addc_co_u32_e64 v163, s[42:43], 0, v163, s[50:51]
	v_cmp_gt_i32_e64 s[76:77], v49, v150
	v_addc_co_u32_e64 v156, s[42:43], 0, v156, s[72:73]
	v_cmp_gt_i32_e64 s[50:51], v49, v151
	v_addc_co_u32_e64 v157, s[42:43], 0, v157, s[74:75]
	v_cmp_gt_i32_e64 s[72:73], v49, v152
	v_addc_co_u32_e64 v158, s[42:43], 0, v158, s[76:77]
	v_cmp_gt_i32_e64 s[74:75], v49, v153
	v_addc_co_u32_e64 v159, s[42:43], 0, v159, s[50:51]
	v_cmp_gt_i32_e64 s[76:77], v49, v154
	v_addc_co_u32_e64 v160, s[42:43], 0, v160, s[72:73]
	v_cmp_gt_i32_e64 s[50:51], v49, v155
	v_addc_co_u32_e64 v161, s[42:43], 0, v161, s[74:75]
	v_cmp_gt_i32_e64 s[72:73], v50, v140
	v_addc_co_u32_e64 v162, s[42:43], 0, v162, s[76:77]
	v_cmp_gt_i32_e64 s[74:75], v50, v141
	v_addc_co_u32_e64 v163, s[42:43], 0, v163, s[50:51]
	v_cmp_gt_i32_e64 s[76:77], v50, v142
	v_addc_co_u32_e64 v156, s[42:43], 0, v156, s[72:73]
	v_cmp_gt_i32_e64 s[50:51], v50, v151
	v_addc_co_u32_e64 v157, s[42:43], 0, v157, s[74:75]
	v_cmp_gt_i32_e64 s[72:73], v50, v152
	v_addc_co_u32_e64 v158, s[42:43], 0, v158, s[76:77]
	v_cmp_gt_i32_e64 s[74:75], v50, v153
	v_addc_co_u32_e64 v159, s[42:43], 0, v159, s[50:51]
	v_cmp_gt_i32_e64 s[76:77], v50, v154
	v_addc_co_u32_e64 v160, s[42:43], 0, v160, s[72:73]
	v_cmp_gt_i32_e64 s[50:51], v50, v155
	v_addc_co_u32_e64 v161, s[42:43], 0, v161, s[74:75]
	v_cmp_gt_i32_e64 s[72:73], v51, v140
	v_addc_co_u32_e64 v162, s[42:43], 0, v162, s[76:77]
	v_cmp_gt_i32_e64 s[74:75], v51, v141
	v_addc_co_u32_e64 v163, s[42:43], 0, v163, s[50:51]
	v_cmp_gt_i32_e64 s[76:77], v51, v142
	v_addc_co_u32_e64 v156, s[42:43], 0, v156, s[72:73]
	v_cmp_gt_i32_e64 s[50:51], v51, v143
	v_addc_co_u32_e64 v157, s[42:43], 0, v157, s[74:75]
	v_cmp_gt_i32_e64 s[72:73], v51, v152
	v_addc_co_u32_e64 v158, s[42:43], 0, v158, s[76:77]
	v_cmp_gt_i32_e64 s[74:75], v51, v153
	v_addc_co_u32_e64 v159, s[42:43], 0, v159, s[50:51]
	v_cmp_gt_i32_e64 s[76:77], v51, v154
	v_addc_co_u32_e64 v160, s[42:43], 0, v160, s[72:73]
	v_cmp_gt_i32_e64 s[50:51], v51, v155
	v_addc_co_u32_e64 v161, s[42:43], 0, v161, s[74:75]
	v_cmp_gt_i32_e64 s[72:73], v52, v140
	v_addc_co_u32_e64 v162, s[42:43], 0, v162, s[76:77]
	v_cmp_gt_i32_e64 s[74:75], v52, v141
	v_addc_co_u32_e64 v163, s[42:43], 0, v163, s[50:51]
	v_cmp_gt_i32_e64 s[76:77], v52, v142
	v_addc_co_u32_e64 v156, s[42:43], 0, v156, s[72:73]
	v_cmp_gt_i32_e64 s[50:51], v52, v143
	v_addc_co_u32_e64 v157, s[42:43], 0, v157, s[74:75]
	v_cmp_gt_i32_e64 s[72:73], v52, v144
	v_addc_co_u32_e64 v158, s[42:43], 0, v158, s[76:77]
	v_cmp_gt_i32_e64 s[74:75], v52, v153
	v_addc_co_u32_e64 v159, s[42:43], 0, v159, s[50:51]
	v_cmp_gt_i32_e64 s[76:77], v52, v154
	v_addc_co_u32_e64 v160, s[42:43], 0, v160, s[72:73]
	v_cmp_gt_i32_e64 s[50:51], v52, v155
	v_addc_co_u32_e64 v161, s[42:43], 0, v161, s[74:75]
	v_cmp_gt_i32_e64 s[72:73], v53, v140
	v_addc_co_u32_e64 v162, s[42:43], 0, v162, s[76:77]
	v_cmp_gt_i32_e64 s[74:75], v53, v141
	v_addc_co_u32_e64 v163, s[42:43], 0, v163, s[50:51]
	v_cmp_gt_i32_e64 s[76:77], v53, v142
	v_addc_co_u32_e64 v156, s[42:43], 0, v156, s[72:73]
	v_cmp_gt_i32_e64 s[50:51], v53, v143
	v_addc_co_u32_e64 v157, s[42:43], 0, v157, s[74:75]
	v_cmp_gt_i32_e64 s[72:73], v53, v144
	v_addc_co_u32_e64 v158, s[42:43], 0, v158, s[76:77]
	v_cmp_gt_i32_e64 s[74:75], v53, v145
	v_addc_co_u32_e64 v159, s[42:43], 0, v159, s[50:51]
	v_cmp_gt_i32_e64 s[76:77], v53, v154
	v_addc_co_u32_e64 v160, s[42:43], 0, v160, s[72:73]
	v_cmp_gt_i32_e64 s[50:51], v53, v155
	v_addc_co_u32_e64 v161, s[42:43], 0, v161, s[74:75]
	v_cmp_gt_i32_e64 s[72:73], v54, v140
	v_addc_co_u32_e64 v162, s[42:43], 0, v162, s[76:77]
	v_cmp_gt_i32_e64 s[74:75], v54, v141
	v_addc_co_u32_e64 v163, s[42:43], 0, v163, s[50:51]
	v_cmp_gt_i32_e64 s[76:77], v54, v142
	v_addc_co_u32_e64 v156, s[42:43], 0, v156, s[72:73]
	v_cmp_gt_i32_e64 s[50:51], v54, v143
	v_addc_co_u32_e64 v157, s[42:43], 0, v157, s[74:75]
	v_cmp_gt_i32_e64 s[72:73], v54, v144
	v_addc_co_u32_e64 v158, s[42:43], 0, v158, s[76:77]
	v_cmp_gt_i32_e64 s[74:75], v54, v145
	v_addc_co_u32_e64 v159, s[42:43], 0, v159, s[50:51]
	v_cmp_gt_i32_e64 s[76:77], v54, v146
	v_addc_co_u32_e64 v160, s[42:43], 0, v160, s[72:73]
	v_cmp_gt_i32_e64 s[50:51], v54, v155
	v_addc_co_u32_e64 v161, s[42:43], 0, v161, s[74:75]
	v_cmp_gt_i32_e64 s[72:73], v55, v140
	v_addc_co_u32_e64 v162, s[42:43], 0, v162, s[76:77]
	v_cmp_gt_i32_e64 s[74:75], v55, v141
	v_addc_co_u32_e64 v163, s[42:43], 0, v163, s[50:51]
	v_cmp_gt_i32_e64 s[76:77], v55, v142
	v_addc_co_u32_e64 v156, s[42:43], 0, v156, s[72:73]
	v_cmp_gt_i32_e64 s[50:51], v55, v143
	v_addc_co_u32_e64 v157, s[42:43], 0, v157, s[74:75]
	v_cmp_gt_i32_e64 s[72:73], v55, v144
	v_addc_co_u32_e64 v158, s[42:43], 0, v158, s[76:77]
	v_cmp_gt_i32_e64 s[74:75], v55, v145
	v_addc_co_u32_e64 v159, s[42:43], 0, v159, s[50:51]
	v_cmp_gt_i32_e64 s[76:77], v55, v146
	v_addc_co_u32_e64 v160, s[42:43], 0, v160, s[72:73]
	v_cmp_gt_i32_e64 s[50:51], v55, v147
	v_addc_co_u32_e64 v161, s[42:43], 0, v161, s[74:75]
	v_addc_co_u32_e64 v162, s[42:43], 0, v162, s[76:77]
	v_addc_co_u32_e64 v163, s[42:43], 0, v163, s[50:51]
	s_cmp_gt_u32 40, s9
	s_cbranch_scc1 .Ltopk_oct_done
; DI void task_nsa(const P& p, int layer, int task, bf16_t* sm, int dm) {
;     ...
;     const float imp = cbuf[j * 65 + qq];
;     const bool valid = j <= cur;
;     const bool forced = (j == 0) || (j == cur) || (j == cur - 1);
;     const float score = valid ? imp + (forced ? 1e4f : 0.f) : -1e30f;
;     int rank = 0;
; #pragma unroll 4
;     for (int jp = 0; jp < 64; ++jp) {
;       const float sj = __int_as_float(__builtin_amdgcn_readlane(__float_as_int(score), jp));
;       rank += ((sj > score) || (sj == score && jp < j)) ? 1 : 0;
;     }
;     const unsigned long long mk = __ballot(rank < 16);
	ds_read_b32 v100, v171 offset:51648
	ds_read_b32 v101, v171 offset:51908
	ds_read_b32 v102, v171 offset:52168
	ds_read_b32 v103, v171 offset:52428
	ds_read_b32 v104, v171 offset:52688
	ds_read_b32 v105, v171 offset:52948
	ds_read_b32 v106, v171 offset:53208
	ds_read_b32 v107, v171 offset:53468
	s_cmp_lt_u32 5, s28
	s_cselect_b32 s31, 1, 0
	s_cmp_le_u32 5, s28
	s_cselect_b32 s32, 1, 0
	v_subrev_u32_e32 v140, s31, v116
	v_subrev_u32_e32 v141, s31, v117
	v_subrev_u32_e32 v142, s31, v118
	v_subrev_u32_e32 v143, s31, v119
	v_subrev_u32_e32 v144, s31, v120
	v_subrev_u32_e32 v145, s31, v121
	v_subrev_u32_e32 v146, s31, v122
	v_subrev_u32_e32 v147, s31, v123
	v_subrev_u32_e32 v148, s32, v116
	v_subrev_u32_e32 v149, s32, v117
	v_subrev_u32_e32 v150, s32, v118
	v_subrev_u32_e32 v151, s32, v119
	v_subrev_u32_e32 v152, s32, v120
	v_subrev_u32_e32 v153, s32, v121
	v_subrev_u32_e32 v154, s32, v122
	v_subrev_u32_e32 v155, s32, v123
	s_waitcnt lgkmcnt(8)
	v_cmp_gt_i32_e64 s[72:73], v56, v140
	v_cmp_gt_i32_e64 s[74:75], v56, v149
	v_cmp_gt_i32_e64 s[76:77], v56, v150
	v_addc_co_u32_e64 v156, s[42:43], 0, v156, s[72:73]
	v_cmp_gt_i32_e64 s[50:51], v56, v151
	v_addc_co_u32_e64 v157, s[42:43], 0, v157, s[74:75]
	v_cmp_gt_i32_e64 s[72:73], v56, v152
	v_addc_co_u32_e64 v158, s[42:43], 0, v158, s[76:77]
	v_cmp_gt_i32_e64 s[74:75], v56, v153
	v_addc_co_u32_e64 v159, s[42:43], 0, v159, s[50:51]
	v_cmp_gt_i32_e64 s[76:77], v56, v154
	v_addc_co_u32_e64 v160, s[42:43], 0, v160, s[72:73]
	v_cmp_gt_i32_e64 s[50:51], v56, v155
	v_addc_co_u32_e64 v161, s[42:43], 0, v161, s[74:75]
	v_cmp_gt_i32_e64 s[72:73], v57, v140
	v_addc_co_u32_e64 v162, s[42:43], 0, v162, s[76:77]
	v_cmp_gt_i32_e64 s[74:75], v57, v141
	v_addc_co_u32_e64 v163, s[42:43], 0, v163, s[50:51]
	v_cmp_gt_i32_e64 s[76:77], v57, v150
	v_addc_co_u32_e64 v156, s[42:43], 0, v156, s[72:73]
	v_cmp_gt_i32_e64 s[50:51], v57, v151
	v_addc_co_u32_e64 v157, s[42:43], 0, v157, s[74:75]
	v_cmp_gt_i32_e64 s[72:73], v57, v152
	v_addc_co_u32_e64 v158, s[42:43], 0, v158, s[76:77]
	v_cmp_gt_i32_e64 s[74:75], v57, v153
	v_addc_co_u32_e64 v159, s[42:43], 0, v159, s[50:51]
	v_cmp_gt_i32_e64 s[76:77], v57, v154
	v_addc_co_u32_e64 v160, s[42:43], 0, v160, s[72:73]
	v_cmp_gt_i32_e64 s[50:51], v57, v155
	v_addc_co_u32_e64 v161, s[42:43], 0, v161, s[74:75]
	v_cmp_gt_i32_e64 s[72:73], v58, v140
	v_addc_co_u32_e64 v162, s[42:43], 0, v162, s[76:77]
	v_cmp_gt_i32_e64 s[74:75], v58, v141
	v_addc_co_u32_e64 v163, s[42:43], 0, v163, s[50:51]
	v_cmp_gt_i32_e64 s[76:77], v58, v142
	v_addc_co_u32_e64 v156, s[42:43], 0, v156, s[72:73]
	v_cmp_gt_i32_e64 s[50:51], v58, v151
	v_addc_co_u32_e64 v157, s[42:43], 0, v157, s[74:75]
	v_cmp_gt_i32_e64 s[72:73], v58, v152
	v_addc_co_u32_e64 v158, s[42:43], 0, v158, s[76:77]
	v_cmp_gt_i32_e64 s[74:75], v58, v153
	v_addc_co_u32_e64 v159, s[42:43], 0, v159, s[50:51]
	v_cmp_gt_i32_e64 s[76:77], v58, v154
	v_addc_co_u32_e64 v160, s[42:43], 0, v160, s[72:73]
	v_cmp_gt_i32_e64 s[50:51], v58, v155
	v_addc_co_u32_e64 v161, s[42:43], 0, v161, s[74:75]
	v_cmp_gt_i32_e64 s[72:73], v59, v140
	v_addc_co_u32_e64 v162, s[42:43], 0, v162, s[76:77]
	v_cmp_gt_i32_e64 s[74:75], v59, v141
	v_addc_co_u32_e64 v163, s[42:43], 0, v163, s[50:51]
	v_cmp_gt_i32_e64 s[76:77], v59, v142
	v_addc_co_u32_e64 v156, s[42:43], 0, v156, s[72:73]
	v_cmp_gt_i32_e64 s[50:51], v59, v143
	v_addc_co_u32_e64 v157, s[42:43], 0, v157, s[74:75]
	v_cmp_gt_i32_e64 s[72:73], v59, v152
	v_addc_co_u32_e64 v158, s[42:43], 0, v158, s[76:77]
	v_cmp_gt_i32_e64 s[74:75], v59, v153
	v_addc_co_u32_e64 v159, s[42:43], 0, v159, s[50:51]
	v_cmp_gt_i32_e64 s[76:77], v59, v154
	v_addc_co_u32_e64 v160, s[42:43], 0, v160, s[72:73]
	v_cmp_gt_i32_e64 s[50:51], v59, v155
	v_addc_co_u32_e64 v161, s[42:43], 0, v161, s[74:75]
	v_cmp_gt_i32_e64 s[72:73], v60, v140
	v_addc_co_u32_e64 v162, s[42:43], 0, v162, s[76:77]
	v_cmp_gt_i32_e64 s[74:75], v60, v141
	v_addc_co_u32_e64 v163, s[42:43], 0, v163, s[50:51]
	v_cmp_gt_i32_e64 s[76:77], v60, v142
	v_addc_co_u32_e64 v156, s[42:43], 0, v156, s[72:73]
	v_cmp_gt_i32_e64 s[50:51], v60, v143
	v_addc_co_u32_e64 v157, s[42:43], 0, v157, s[74:75]
	v_cmp_gt_i32_e64 s[72:73], v60, v144
	v_addc_co_u32_e64 v158, s[42:43], 0, v158, s[76:77]
	v_cmp_gt_i32_e64 s[74:75], v60, v153
	v_addc_co_u32_e64 v159, s[42:43], 0, v159, s[50:51]
	v_cmp_gt_i32_e64 s[76:77], v60, v154
	v_addc_co_u32_e64 v160, s[42:43], 0, v160, s[72:73]
	v_cmp_gt_i32_e64 s[50:51], v60, v155
	v_addc_co_u32_e64 v161, s[42:43], 0, v161, s[74:75]
	v_cmp_gt_i32_e64 s[72:73], v61, v140
	v_addc_co_u32_e64 v162, s[42:43], 0, v162, s[76:77]
	v_cmp_gt_i32_e64 s[74:75], v61, v141
	v_addc_co_u32_e64 v163, s[42:43], 0, v163, s[50:51]
	v_cmp_gt_i32_e64 s[76:77], v61, v142
	v_addc_co_u32_e64 v156, s[42:43], 0, v156, s[72:73]
	v_cmp_gt_i32_e64 s[50:51], v61, v143
	v_addc_co_u32_e64 v157, s[42:43], 0, v157, s[74:75]
	v_cmp_gt_i32_e64 s[72:73], v61, v144
	v_addc_co_u32_e64 v158, s[42:43], 0, v158, s[76:77]
	v_cmp_gt_i32_e64 s[74:75], v61, v145
	v_addc_co_u32_e64 v159, s[42:43], 0, v159, s[50:51]
	v_cmp_gt_i32_e64 s[76:77], v61, v154
	v_addc_co_u32_e64 v160, s[42:43], 0, v160, s[72:73]
	v_cmp_gt_i32_e64 s[50:51], v61, v155
	v_addc_co_u32_e64 v161, s[42:43], 0, v161, s[74:75]
	v_cmp_gt_i32_e64 s[72:73], v62, v140
	v_addc_co_u32_e64 v162, s[42:43], 0, v162, s[76:77]
	v_cmp_gt_i32_e64 s[74:75], v62, v141
	v_addc_co_u32_e64 v163, s[42:43], 0, v163, s[50:51]
	v_cmp_gt_i32_e64 s[76:77], v62, v142
	v_addc_co_u32_e64 v156, s[42:43], 0, v156, s[72:73]
	v_cmp_gt_i32_e64 s[50:51], v62, v143
	v_addc_co_u32_e64 v157, s[42:43], 0, v157, s[74:75]
	v_cmp_gt_i32_e64 s[72:73], v62, v144
	v_addc_co_u32_e64 v158, s[42:43], 0, v158, s[76:77]
	v_cmp_gt_i32_e64 s[74:75], v62, v145
	v_addc_co_u32_e64 v159, s[42:43], 0, v159, s[50:51]
	v_cmp_gt_i32_e64 s[76:77], v62, v146
	v_addc_co_u32_e64 v160, s[42:43], 0, v160, s[72:73]
	v_cmp_gt_i32_e64 s[50:51], v62, v155
	v_addc_co_u32_e64 v161, s[42:43], 0, v161, s[74:75]
	v_cmp_gt_i32_e64 s[72:73], v63, v140
	v_addc_co_u32_e64 v162, s[42:43], 0, v162, s[76:77]
	v_cmp_gt_i32_e64 s[74:75], v63, v141
	v_addc_co_u32_e64 v163, s[42:43], 0, v163, s[50:51]
	v_cmp_gt_i32_e64 s[76:77], v63, v142
	v_addc_co_u32_e64 v156, s[42:43], 0, v156, s[72:73]
	v_cmp_gt_i32_e64 s[50:51], v63, v143
	v_addc_co_u32_e64 v157, s[42:43], 0, v157, s[74:75]
	v_cmp_gt_i32_e64 s[72:73], v63, v144
	v_addc_co_u32_e64 v158, s[42:43], 0, v158, s[76:77]
	v_cmp_gt_i32_e64 s[74:75], v63, v145
	v_addc_co_u32_e64 v159, s[42:43], 0, v159, s[50:51]
	v_cmp_gt_i32_e64 s[76:77], v63, v146
	v_addc_co_u32_e64 v160, s[42:43], 0, v160, s[72:73]
	v_cmp_gt_i32_e64 s[50:51], v63, v147
	v_addc_co_u32_e64 v161, s[42:43], 0, v161, s[74:75]
	v_addc_co_u32_e64 v162, s[42:43], 0, v162, s[76:77]
	v_addc_co_u32_e64 v163, s[42:43], 0, v163, s[50:51]
	s_cmp_gt_u32 48, s9
	s_cbranch_scc1 .Ltopk_oct_done
; DI void task_nsa(const P& p, int layer, int task, bf16_t* sm, int dm) {
;     ...
;     const float imp = cbuf[j * 65 + qq];
;     const bool valid = j <= cur;
;     const bool forced = (j == 0) || (j == cur) || (j == cur - 1);
;     const float score = valid ? imp + (forced ? 1e4f : 0.f) : -1e30f;
;     int rank = 0;
; #pragma unroll 4
;     for (int jp = 0; jp < 64; ++jp) {
;       const float sj = __int_as_float(__builtin_amdgcn_readlane(__float_as_int(score), jp));
;       rank += ((sj > score) || (sj == score && jp < j)) ? 1 : 0;
;     }
;     const unsigned long long mk = __ballot(rank < 16);
	ds_read_b32 v108, v171 offset:53728
	ds_read_b32 v109, v171 offset:53988
	ds_read_b32 v110, v171 offset:54248
	ds_read_b32 v111, v171 offset:54508
	ds_read_b32 v112, v171 offset:54768
	ds_read_b32 v113, v171 offset:55028
	ds_read_b32 v114, v171 offset:55288
	ds_read_b32 v115, v171 offset:55548
	s_cmp_lt_u32 6, s28
	s_cselect_b32 s31, 1, 0
	s_cmp_le_u32 6, s28
	s_cselect_b32 s32, 1, 0
	v_subrev_u32_e32 v140, s31, v116
	v_subrev_u32_e32 v141, s31, v117
	v_subrev_u32_e32 v142, s31, v118
	v_subrev_u32_e32 v143, s31, v119
	v_subrev_u32_e32 v144, s31, v120
	v_subrev_u32_e32 v145, s31, v121
	v_subrev_u32_e32 v146, s31, v122
	v_subrev_u32_e32 v147, s31, v123
	v_subrev_u32_e32 v148, s32, v116
	v_subrev_u32_e32 v149, s32, v117
	v_subrev_u32_e32 v150, s32, v118
	v_subrev_u32_e32 v151, s32, v119
	v_subrev_u32_e32 v152, s32, v120
	v_subrev_u32_e32 v153, s32, v121
	v_subrev_u32_e32 v154, s32, v122
	v_subrev_u32_e32 v155, s32, v123
	s_waitcnt lgkmcnt(8)
	v_cmp_gt_i32_e64 s[72:73], v100, v140
	v_cmp_gt_i32_e64 s[74:75], v100, v149
	v_cmp_gt_i32_e64 s[76:77], v100, v150
	v_addc_co_u32_e64 v156, s[42:43], 0, v156, s[72:73]
	v_cmp_gt_i32_e64 s[50:51], v100, v151
	v_addc_co_u32_e64 v157, s[42:43], 0, v157, s[74:75]
	v_cmp_gt_i32_e64 s[72:73], v100, v152
	v_addc_co_u32_e64 v158, s[42:43], 0, v158, s[76:77]
	v_cmp_gt_i32_e64 s[74:75], v100, v153
	v_addc_co_u32_e64 v159, s[42:43], 0, v159, s[50:51]
	v_cmp_gt_i32_e64 s[76:77], v100, v154
	v_addc_co_u32_e64 v160, s[42:43], 0, v160, s[72:73]
	v_cmp_gt_i32_e64 s[50:51], v100, v155
	v_addc_co_u32_e64 v161, s[42:43], 0, v161, s[74:75]
	v_cmp_gt_i32_e64 s[72:73], v101, v140
	v_addc_co_u32_e64 v162, s[42:43], 0, v162, s[76:77]
	v_cmp_gt_i32_e64 s[74:75], v101, v141
	v_addc_co_u32_e64 v163, s[42:43], 0, v163, s[50:51]
	v_cmp_gt_i32_e64 s[76:77], v101, v150
	v_addc_co_u32_e64 v156, s[42:43], 0, v156, s[72:73]
	v_cmp_gt_i32_e64 s[50:51], v101, v151
	v_addc_co_u32_e64 v157, s[42:43], 0, v157, s[74:75]
	v_cmp_gt_i32_e64 s[72:73], v101, v152
	v_addc_co_u32_e64 v158, s[42:43], 0, v158, s[76:77]
	v_cmp_gt_i32_e64 s[74:75], v101, v153
	v_addc_co_u32_e64 v159, s[42:43], 0, v159, s[50:51]
	v_cmp_gt_i32_e64 s[76:77], v101, v154
	v_addc_co_u32_e64 v160, s[42:43], 0, v160, s[72:73]
	v_cmp_gt_i32_e64 s[50:51], v101, v155
	v_addc_co_u32_e64 v161, s[42:43], 0, v161, s[74:75]
	v_cmp_gt_i32_e64 s[72:73], v102, v140
	v_addc_co_u32_e64 v162, s[42:43], 0, v162, s[76:77]
	v_cmp_gt_i32_e64 s[74:75], v102, v141
	v_addc_co_u32_e64 v163, s[42:43], 0, v163, s[50:51]
	v_cmp_gt_i32_e64 s[76:77], v102, v142
	v_addc_co_u32_e64 v156, s[42:43], 0, v156, s[72:73]
	v_cmp_gt_i32_e64 s[50:51], v102, v151
	v_addc_co_u32_e64 v157, s[42:43], 0, v157, s[74:75]
	v_cmp_gt_i32_e64 s[72:73], v102, v152
	v_addc_co_u32_e64 v158, s[42:43], 0, v158, s[76:77]
	v_cmp_gt_i32_e64 s[74:75], v102, v153
	v_addc_co_u32_e64 v159, s[42:43], 0, v159, s[50:51]
	v_cmp_gt_i32_e64 s[76:77], v102, v154
	v_addc_co_u32_e64 v160, s[42:43], 0, v160, s[72:73]
	v_cmp_gt_i32_e64 s[50:51], v102, v155
	v_addc_co_u32_e64 v161, s[42:43], 0, v161, s[74:75]
	v_cmp_gt_i32_e64 s[72:73], v103, v140
	v_addc_co_u32_e64 v162, s[42:43], 0, v162, s[76:77]
	v_cmp_gt_i32_e64 s[74:75], v103, v141
	v_addc_co_u32_e64 v163, s[42:43], 0, v163, s[50:51]
	v_cmp_gt_i32_e64 s[76:77], v103, v142
	v_addc_co_u32_e64 v156, s[42:43], 0, v156, s[72:73]
	v_cmp_gt_i32_e64 s[50:51], v103, v143
	v_addc_co_u32_e64 v157, s[42:43], 0, v157, s[74:75]
	v_cmp_gt_i32_e64 s[72:73], v103, v152
	v_addc_co_u32_e64 v158, s[42:43], 0, v158, s[76:77]
	v_cmp_gt_i32_e64 s[74:75], v103, v153
	v_addc_co_u32_e64 v159, s[42:43], 0, v159, s[50:51]
	v_cmp_gt_i32_e64 s[76:77], v103, v154
	v_addc_co_u32_e64 v160, s[42:43], 0, v160, s[72:73]
	v_cmp_gt_i32_e64 s[50:51], v103, v155
	v_addc_co_u32_e64 v161, s[42:43], 0, v161, s[74:75]
	v_cmp_gt_i32_e64 s[72:73], v104, v140
	v_addc_co_u32_e64 v162, s[42:43], 0, v162, s[76:77]
	v_cmp_gt_i32_e64 s[74:75], v104, v141
	v_addc_co_u32_e64 v163, s[42:43], 0, v163, s[50:51]
	v_cmp_gt_i32_e64 s[76:77], v104, v142
	v_addc_co_u32_e64 v156, s[42:43], 0, v156, s[72:73]
	v_cmp_gt_i32_e64 s[50:51], v104, v143
	v_addc_co_u32_e64 v157, s[42:43], 0, v157, s[74:75]
	v_cmp_gt_i32_e64 s[72:73], v104, v144
	v_addc_co_u32_e64 v158, s[42:43], 0, v158, s[76:77]
	v_cmp_gt_i32_e64 s[74:75], v104, v153
	v_addc_co_u32_e64 v159, s[42:43], 0, v159, s[50:51]
	v_cmp_gt_i32_e64 s[76:77], v104, v154
	v_addc_co_u32_e64 v160, s[42:43], 0, v160, s[72:73]
	v_cmp_gt_i32_e64 s[50:51], v104, v155
	v_addc_co_u32_e64 v161, s[42:43], 0, v161, s[74:75]
	v_cmp_gt_i32_e64 s[72:73], v105, v140
	v_addc_co_u32_e64 v162, s[42:43], 0, v162, s[76:77]
	v_cmp_gt_i32_e64 s[74:75], v105, v141
	v_addc_co_u32_e64 v163, s[42:43], 0, v163, s[50:51]
	v_cmp_gt_i32_e64 s[76:77], v105, v142
	v_addc_co_u32_e64 v156, s[42:43], 0, v156, s[72:73]
	v_cmp_gt_i32_e64 s[50:51], v105, v143
	v_addc_co_u32_e64 v157, s[42:43], 0, v157, s[74:75]
	v_cmp_gt_i32_e64 s[72:73], v105, v144
	v_addc_co_u32_e64 v158, s[42:43], 0, v158, s[76:77]
	v_cmp_gt_i32_e64 s[74:75], v105, v145
	v_addc_co_u32_e64 v159, s[42:43], 0, v159, s[50:51]
	v_cmp_gt_i32_e64 s[76:77], v105, v154
	v_addc_co_u32_e64 v160, s[42:43], 0, v160, s[72:73]
	v_cmp_gt_i32_e64 s[50:51], v105, v155
	v_addc_co_u32_e64 v161, s[42:43], 0, v161, s[74:75]
	v_cmp_gt_i32_e64 s[72:73], v106, v140
	v_addc_co_u32_e64 v162, s[42:43], 0, v162, s[76:77]
	v_cmp_gt_i32_e64 s[74:75], v106, v141
	v_addc_co_u32_e64 v163, s[42:43], 0, v163, s[50:51]
	v_cmp_gt_i32_e64 s[76:77], v106, v142
	v_addc_co_u32_e64 v156, s[42:43], 0, v156, s[72:73]
	v_cmp_gt_i32_e64 s[50:51], v106, v143
	v_addc_co_u32_e64 v157, s[42:43], 0, v157, s[74:75]
	v_cmp_gt_i32_e64 s[72:73], v106, v144
	v_addc_co_u32_e64 v158, s[42:43], 0, v158, s[76:77]
	v_cmp_gt_i32_e64 s[74:75], v106, v145
	v_addc_co_u32_e64 v159, s[42:43], 0, v159, s[50:51]
	v_cmp_gt_i32_e64 s[76:77], v106, v146
	v_addc_co_u32_e64 v160, s[42:43], 0, v160, s[72:73]
	v_cmp_gt_i32_e64 s[50:51], v106, v155
	v_addc_co_u32_e64 v161, s[42:43], 0, v161, s[74:75]
	v_cmp_gt_i32_e64 s[72:73], v107, v140
	v_addc_co_u32_e64 v162, s[42:43], 0, v162, s[76:77]
	v_cmp_gt_i32_e64 s[74:75], v107, v141
	v_addc_co_u32_e64 v163, s[42:43], 0, v163, s[50:51]
	v_cmp_gt_i32_e64 s[76:77], v107, v142
	v_addc_co_u32_e64 v156, s[42:43], 0, v156, s[72:73]
	v_cmp_gt_i32_e64 s[50:51], v107, v143
	v_addc_co_u32_e64 v157, s[42:43], 0, v157, s[74:75]
	v_cmp_gt_i32_e64 s[72:73], v107, v144
	v_addc_co_u32_e64 v158, s[42:43], 0, v158, s[76:77]
	v_cmp_gt_i32_e64 s[74:75], v107, v145
	v_addc_co_u32_e64 v159, s[42:43], 0, v159, s[50:51]
	v_cmp_gt_i32_e64 s[76:77], v107, v146
	v_addc_co_u32_e64 v160, s[42:43], 0, v160, s[72:73]
	v_cmp_gt_i32_e64 s[50:51], v107, v147
	v_addc_co_u32_e64 v161, s[42:43], 0, v161, s[74:75]
	v_addc_co_u32_e64 v162, s[42:43], 0, v162, s[76:77]
	v_addc_co_u32_e64 v163, s[42:43], 0, v163, s[50:51]
	s_cmp_gt_u32 56, s9
	s_cbranch_scc1 .Ltopk_oct_done
; DI void task_nsa(const P& p, int layer, int task, bf16_t* sm, int dm) {
;     ...
;     const float imp = cbuf[j * 65 + qq];
;     const bool valid = j <= cur;
;     const bool forced = (j == 0) || (j == cur) || (j == cur - 1);
;     const float score = valid ? imp + (forced ? 1e4f : 0.f) : -1e30f;
;     int rank = 0;
; #pragma unroll 4
;     for (int jp = 0; jp < 64; ++jp) {
;       const float sj = __int_as_float(__builtin_amdgcn_readlane(__float_as_int(score), jp));
;       rank += ((sj > score) || (sj == score && jp < j)) ? 1 : 0;
;     }
;     const unsigned long long mk = __ballot(rank < 16);
	s_cmp_lt_u32 7, s28
	s_cselect_b32 s31, 1, 0
	s_cmp_le_u32 7, s28
	s_cselect_b32 s32, 1, 0
	v_subrev_u32_e32 v140, s31, v116
	v_subrev_u32_e32 v141, s31, v117
	v_subrev_u32_e32 v142, s31, v118
	v_subrev_u32_e32 v143, s31, v119
	v_subrev_u32_e32 v144, s31, v120
	v_subrev_u32_e32 v145, s31, v121
	v_subrev_u32_e32 v146, s31, v122
	v_subrev_u32_e32 v147, s31, v123
	v_subrev_u32_e32 v148, s32, v116
	v_subrev_u32_e32 v149, s32, v117
	v_subrev_u32_e32 v150, s32, v118
	v_subrev_u32_e32 v151, s32, v119
	v_subrev_u32_e32 v152, s32, v120
	v_subrev_u32_e32 v153, s32, v121
	v_subrev_u32_e32 v154, s32, v122
	v_subrev_u32_e32 v155, s32, v123
	s_waitcnt lgkmcnt(0)
	v_cmp_gt_i32_e64 s[72:73], v108, v140
	v_cmp_gt_i32_e64 s[74:75], v108, v149
	v_cmp_gt_i32_e64 s[76:77], v108, v150
	v_addc_co_u32_e64 v156, s[42:43], 0, v156, s[72:73]
	v_cmp_gt_i32_e64 s[50:51], v108, v151
	v_addc_co_u32_e64 v157, s[42:43], 0, v157, s[74:75]
	v_cmp_gt_i32_e64 s[72:73], v108, v152
	v_addc_co_u32_e64 v158, s[42:43], 0, v158, s[76:77]
	v_cmp_gt_i32_e64 s[74:75], v108, v153
	v_addc_co_u32_e64 v159, s[42:43], 0, v159, s[50:51]
	v_cmp_gt_i32_e64 s[76:77], v108, v154
	v_addc_co_u32_e64 v160, s[42:43], 0, v160, s[72:73]
	v_cmp_gt_i32_e64 s[50:51], v108, v155
	v_addc_co_u32_e64 v161, s[42:43], 0, v161, s[74:75]
	v_cmp_gt_i32_e64 s[72:73], v109, v140
	v_addc_co_u32_e64 v162, s[42:43], 0, v162, s[76:77]
	v_cmp_gt_i32_e64 s[74:75], v109, v141
	v_addc_co_u32_e64 v163, s[42:43], 0, v163, s[50:51]
	v_cmp_gt_i32_e64 s[76:77], v109, v150
	v_addc_co_u32_e64 v156, s[42:43], 0, v156, s[72:73]
	v_cmp_gt_i32_e64 s[50:51], v109, v151
	v_addc_co_u32_e64 v157, s[42:43], 0, v157, s[74:75]
	v_cmp_gt_i32_e64 s[72:73], v109, v152
	v_addc_co_u32_e64 v158, s[42:43], 0, v158, s[76:77]
	v_cmp_gt_i32_e64 s[74:75], v109, v153
	v_addc_co_u32_e64 v159, s[42:43], 0, v159, s[50:51]
	v_cmp_gt_i32_e64 s[76:77], v109, v154
	v_addc_co_u32_e64 v160, s[42:43], 0, v160, s[72:73]
	v_cmp_gt_i32_e64 s[50:51], v109, v155
	v_addc_co_u32_e64 v161, s[42:43], 0, v161, s[74:75]
	v_cmp_gt_i32_e64 s[72:73], v110, v140
	v_addc_co_u32_e64 v162, s[42:43], 0, v162, s[76:77]
	v_cmp_gt_i32_e64 s[74:75], v110, v141
	v_addc_co_u32_e64 v163, s[42:43], 0, v163, s[50:51]
	v_cmp_gt_i32_e64 s[76:77], v110, v142
	v_addc_co_u32_e64 v156, s[42:43], 0, v156, s[72:73]
	v_cmp_gt_i32_e64 s[50:51], v110, v151
	v_addc_co_u32_e64 v157, s[42:43], 0, v157, s[74:75]
	v_cmp_gt_i32_e64 s[72:73], v110, v152
	v_addc_co_u32_e64 v158, s[42:43], 0, v158, s[76:77]
	v_cmp_gt_i32_e64 s[74:75], v110, v153
	v_addc_co_u32_e64 v159, s[42:43], 0, v159, s[50:51]
	v_cmp_gt_i32_e64 s[76:77], v110, v154
	v_addc_co_u32_e64 v160, s[42:43], 0, v160, s[72:73]
	v_cmp_gt_i32_e64 s[50:51], v110, v155
	v_addc_co_u32_e64 v161, s[42:43], 0, v161, s[74:75]
	v_cmp_gt_i32_e64 s[72:73], v111, v140
	v_addc_co_u32_e64 v162, s[42:43], 0, v162, s[76:77]
	v_cmp_gt_i32_e64 s[74:75], v111, v141
	v_addc_co_u32_e64 v163, s[42:43], 0, v163, s[50:51]
	v_cmp_gt_i32_e64 s[76:77], v111, v142
	v_addc_co_u32_e64 v156, s[42:43], 0, v156, s[72:73]
	v_cmp_gt_i32_e64 s[50:51], v111, v143
	v_addc_co_u32_e64 v157, s[42:43], 0, v157, s[74:75]
	v_cmp_gt_i32_e64 s[72:73], v111, v152
	v_addc_co_u32_e64 v158, s[42:43], 0, v158, s[76:77]
	v_cmp_gt_i32_e64 s[74:75], v111, v153
	v_addc_co_u32_e64 v159, s[42:43], 0, v159, s[50:51]
	v_cmp_gt_i32_e64 s[76:77], v111, v154
	v_addc_co_u32_e64 v160, s[42:43], 0, v160, s[72:73]
	v_cmp_gt_i32_e64 s[50:51], v111, v155
	v_addc_co_u32_e64 v161, s[42:43], 0, v161, s[74:75]
	v_cmp_gt_i32_e64 s[72:73], v112, v140
	v_addc_co_u32_e64 v162, s[42:43], 0, v162, s[76:77]
	v_cmp_gt_i32_e64 s[74:75], v112, v141
	v_addc_co_u32_e64 v163, s[42:43], 0, v163, s[50:51]
	v_cmp_gt_i32_e64 s[76:77], v112, v142
	v_addc_co_u32_e64 v156, s[42:43], 0, v156, s[72:73]
	v_cmp_gt_i32_e64 s[50:51], v112, v143
	v_addc_co_u32_e64 v157, s[42:43], 0, v157, s[74:75]
	v_cmp_gt_i32_e64 s[72:73], v112, v144
	v_addc_co_u32_e64 v158, s[42:43], 0, v158, s[76:77]
	v_cmp_gt_i32_e64 s[74:75], v112, v153
	v_addc_co_u32_e64 v159, s[42:43], 0, v159, s[50:51]
	v_cmp_gt_i32_e64 s[76:77], v112, v154
	v_addc_co_u32_e64 v160, s[42:43], 0, v160, s[72:73]
	v_cmp_gt_i32_e64 s[50:51], v112, v155
	v_addc_co_u32_e64 v161, s[42:43], 0, v161, s[74:75]
	v_cmp_gt_i32_e64 s[72:73], v113, v140
	v_addc_co_u32_e64 v162, s[42:43], 0, v162, s[76:77]
	v_cmp_gt_i32_e64 s[74:75], v113, v141
	v_addc_co_u32_e64 v163, s[42:43], 0, v163, s[50:51]
	v_cmp_gt_i32_e64 s[76:77], v113, v142
	v_addc_co_u32_e64 v156, s[42:43], 0, v156, s[72:73]
	v_cmp_gt_i32_e64 s[50:51], v113, v143
	v_addc_co_u32_e64 v157, s[42:43], 0, v157, s[74:75]
	v_cmp_gt_i32_e64 s[72:73], v113, v144
	v_addc_co_u32_e64 v158, s[42:43], 0, v158, s[76:77]
	v_cmp_gt_i32_e64 s[74:75], v113, v145
	v_addc_co_u32_e64 v159, s[42:43], 0, v159, s[50:51]
	v_cmp_gt_i32_e64 s[76:77], v113, v154
	v_addc_co_u32_e64 v160, s[42:43], 0, v160, s[72:73]
	v_cmp_gt_i32_e64 s[50:51], v113, v155
	v_addc_co_u32_e64 v161, s[42:43], 0, v161, s[74:75]
	v_cmp_gt_i32_e64 s[72:73], v114, v140
	v_addc_co_u32_e64 v162, s[42:43], 0, v162, s[76:77]
	v_cmp_gt_i32_e64 s[74:75], v114, v141
	v_addc_co_u32_e64 v163, s[42:43], 0, v163, s[50:51]
	v_cmp_gt_i32_e64 s[76:77], v114, v142
	v_addc_co_u32_e64 v156, s[42:43], 0, v156, s[72:73]
	v_cmp_gt_i32_e64 s[50:51], v114, v143
	v_addc_co_u32_e64 v157, s[42:43], 0, v157, s[74:75]
	v_cmp_gt_i32_e64 s[72:73], v114, v144
	v_addc_co_u32_e64 v158, s[42:43], 0, v158, s[76:77]
	v_cmp_gt_i32_e64 s[74:75], v114, v145
	v_addc_co_u32_e64 v159, s[42:43], 0, v159, s[50:51]
	v_cmp_gt_i32_e64 s[76:77], v114, v146
	v_addc_co_u32_e64 v160, s[42:43], 0, v160, s[72:73]
	v_cmp_gt_i32_e64 s[50:51], v114, v155
	v_addc_co_u32_e64 v161, s[42:43], 0, v161, s[74:75]
	v_cmp_gt_i32_e64 s[72:73], v115, v140
	v_addc_co_u32_e64 v162, s[42:43], 0, v162, s[76:77]
	v_cmp_gt_i32_e64 s[74:75], v115, v141
	v_addc_co_u32_e64 v163, s[42:43], 0, v163, s[50:51]
	v_cmp_gt_i32_e64 s[76:77], v115, v142
	v_addc_co_u32_e64 v156, s[42:43], 0, v156, s[72:73]
	v_cmp_gt_i32_e64 s[50:51], v115, v143
	v_addc_co_u32_e64 v157, s[42:43], 0, v157, s[74:75]
	v_cmp_gt_i32_e64 s[72:73], v115, v144
	v_addc_co_u32_e64 v158, s[42:43], 0, v158, s[76:77]
	v_cmp_gt_i32_e64 s[74:75], v115, v145
	v_addc_co_u32_e64 v159, s[42:43], 0, v159, s[50:51]
	v_cmp_gt_i32_e64 s[76:77], v115, v146
	v_addc_co_u32_e64 v160, s[42:43], 0, v160, s[72:73]
	v_cmp_gt_i32_e64 s[50:51], v115, v147
	v_addc_co_u32_e64 v161, s[42:43], 0, v161, s[74:75]
	v_addc_co_u32_e64 v162, s[42:43], 0, v162, s[76:77]
	v_addc_co_u32_e64 v163, s[42:43], 0, v163, s[50:51]
